# v23 + hand-scheduled FFN-up epilogue (interleaved rinv chains, stage-wise exp/rcp) + ssm_out carried-state section with all 24 fragment loads hoisted
# baseline (speedup 1.0000x reference)
; __device__ __forceinline__ f32x4 mfma16(bf16x8 a, bf16x8 b, f32x4 c) { return __builtin_amdgcn_mfma_f32_16x16x32_bf16(a, b, c, 0, 0, 0); }
; __device__ __forceinline__ void ssm_out_unit(const Args& a, int unit) {
;     ...
; #pragma unroll
;     for (int kb = 0; kb < 4; ++kb) {
;         bf16x8 af[2];
; #pragma unroll
;         for (int rk = 0; rk < 2; ++rk) af[rk] = *(const bf16x8*)(HC + ((size_t)(wave * 32 + rk * 16 + r16) * 32 + g) * 128 + kb * 32 + quad * 8);
; #pragma unroll
;         for (int nb = 0; nb < 4; ++nb) { const bf16x8 bf = *(const bf16x8*)(MCT + ((size_t)g * 1024 + (cb * 4 + nb) * 16 + r16) * 128 + kb * 32 + quad * 8);
;             acc[0][nb] = mfma16(af[0], bf, acc[0][nb]); acc[1][nb] = mfma16(af[1], bf, acc[1][nb]); }
;     }
.LBB0_271:
	v_readlane_b32 s0, v251, 10
	v_readlane_b32 s1, v251, 11
	v_lshlrev_b32_e32 v136, 4, v154
	v_lshl_or_b32 v210, v157, 5, v156
	v_ashrrev_i32_e32 v211, 31, v210
	v_lshl_add_u64 v[212:213], s[0:1], 0, v[136:137]
	v_lshlrev_b64 v[214:215], 13, v[210:211]
	v_lshl_add_u64 v[214:215], v[212:213], 0, v[214:215]
	v_or_b32_e32 v210, 16, v210
	v_ashrrev_i32_e32 v211, 31, v210
	v_lshlrev_b64 v[216:217], 13, v[210:211]
	v_lshl_add_u64 v[216:217], v[212:213], 0, v[216:217]
	v_readlane_b32 s0, v251, 16
	v_readlane_b32 s1, v251, 17
	s_nop 1
	v_or_b32_e32 v218, s0, v156
	v_mov_b32_e32 v221, s1
	v_readlane_b32 s0, v251, 8
	v_readlane_b32 s1, v251, 9
	s_nop 1
	v_lshl_add_u64 v[222:223], s[0:1], 0, v[136:137]
	v_readlane_b32 s0, v251, 14
	s_nop 1
	v_or_b32_e32 v220, s0, v218
	v_lshlrev_b64 v[224:225], 8, v[220:221]
	v_lshl_add_u64 v[224:225], v[222:223], 0, v[224:225]
	v_readlane_b32 s0, v251, 12
	s_nop 1
	v_or_b32_e32 v220, s0, v218
	v_lshlrev_b64 v[226:227], 8, v[220:221]
	v_lshl_add_u64 v[226:227], v[222:223], 0, v[226:227]
	v_readlane_b32 s0, v251, 13
	s_nop 1
	v_or_b32_e32 v220, s0, v218
	v_lshlrev_b64 v[228:229], 8, v[220:221]
	v_lshl_add_u64 v[228:229], v[222:223], 0, v[228:229]
	v_readlane_b32 s0, v251, 15
	s_nop 1
	v_or_b32_e32 v220, s0, v218
	v_lshlrev_b64 v[230:231], 8, v[220:221]
	v_lshl_add_u64 v[230:231], v[222:223], 0, v[230:231]
	global_load_dwordx4 v[32:35], v[214:215], off
	global_load_dwordx4 v[36:39], v[216:217], off
	global_load_dwordx4 v[40:43], v[224:225], off
	global_load_dwordx4 v[44:47], v[226:227], off
	global_load_dwordx4 v[48:51], v[228:229], off
	global_load_dwordx4 v[52:55], v[230:231], off
	global_load_dwordx4 v[56:59], v[214:215], off offset:64
	global_load_dwordx4 v[60:63], v[216:217], off offset:64
	global_load_dwordx4 v[64:67], v[224:225], off offset:64
	global_load_dwordx4 v[68:71], v[226:227], off offset:64
	global_load_dwordx4 v[72:75], v[228:229], off offset:64
	global_load_dwordx4 v[76:79], v[230:231], off offset:64
	global_load_dwordx4 v[80:83], v[214:215], off offset:128
	global_load_dwordx4 v[84:87], v[216:217], off offset:128
	global_load_dwordx4 v[88:91], v[224:225], off offset:128
	global_load_dwordx4 v[92:95], v[226:227], off offset:128
	global_load_dwordx4 v[96:99], v[228:229], off offset:128
	global_load_dwordx4 v[100:103], v[230:231], off offset:128
	global_load_dwordx4 v[104:107], v[214:215], off offset:192
	global_load_dwordx4 v[108:111], v[216:217], off offset:192
	global_load_dwordx4 v[112:115], v[224:225], off offset:192
	global_load_dwordx4 v[116:119], v[226:227], off offset:192
	global_load_dwordx4 v[120:123], v[228:229], off offset:192
	global_load_dwordx4 v[124:127], v[230:231], off offset:192
	v_lshlrev_b32_e32 v136, 1, v156
	v_readlane_b32 s4, v251, 23
	v_readlane_b32 s8, v251, 25
	v_readlane_b32 s0, v251, 18
	v_readlane_b32 s1, v251, 19
	s_waitcnt vmcnt(18)
	v_mfma_f32_16x16x32_bf16 v[202:205], v[32:35], v[40:43], v[16:19]
	v_mfma_f32_16x16x32_bf16 v[16:19], v[32:35], v[52:55], v[12:15]
	v_mfma_f32_16x16x32_bf16 v[12:15], v[36:39], v[40:43], v[28:31]
	v_mfma_f32_16x16x32_bf16 v[206:209], v[32:35], v[44:47], v[4:7]
	v_mfma_f32_16x16x32_bf16 v[4:7], v[36:39], v[48:51], v[8:11]
	v_mfma_f32_16x16x32_bf16 v[8:11], v[36:39], v[44:47], v[20:23]
	v_mfma_f32_16x16x32_bf16 v[20:23], v[32:35], v[48:51], v[0:3]
	v_mfma_f32_16x16x32_bf16 v[0:3], v[36:39], v[52:55], v[24:27]
	s_waitcnt vmcnt(12)
	v_mfma_f32_16x16x32_bf16 v[28:31], v[56:59], v[64:67], v[202:205]
	v_mfma_f32_16x16x32_bf16 v[16:19], v[56:59], v[76:79], v[16:19]
	v_mfma_f32_16x16x32_bf16 v[12:15], v[60:63], v[64:67], v[12:15]
	v_mfma_f32_16x16x32_bf16 v[24:27], v[56:59], v[68:71], v[206:209]
	v_mfma_f32_16x16x32_bf16 v[4:7], v[60:63], v[72:75], v[4:7]
	v_mfma_f32_16x16x32_bf16 v[8:11], v[60:63], v[68:71], v[8:11]
	v_mfma_f32_16x16x32_bf16 v[20:23], v[56:59], v[72:75], v[20:23]
	v_mfma_f32_16x16x32_bf16 v[0:3], v[60:63], v[76:79], v[0:3]
	s_waitcnt vmcnt(6)
	v_mfma_f32_16x16x32_bf16 v[28:31], v[80:83], v[88:91], v[28:31]
	v_mfma_f32_16x16x32_bf16 v[16:19], v[80:83], v[100:103], v[16:19]
	v_mfma_f32_16x16x32_bf16 v[12:15], v[84:87], v[88:91], v[12:15]
	v_mfma_f32_16x16x32_bf16 v[24:27], v[80:83], v[92:95], v[24:27]
	v_mfma_f32_16x16x32_bf16 v[4:7], v[84:87], v[96:99], v[4:7]
	v_mfma_f32_16x16x32_bf16 v[8:11], v[84:87], v[92:95], v[8:11]
	v_mfma_f32_16x16x32_bf16 v[20:23], v[80:83], v[96:99], v[20:23]
	v_mfma_f32_16x16x32_bf16 v[0:3], v[84:87], v[100:103], v[0:3]
	s_waitcnt vmcnt(0)
; __device__ __forceinline__ unsigned f2bf(float f) { return pk2(f, 0.f) & 0xffffu; }
; __device__ __forceinline__ f32x4 mfma16(bf16x8 a, bf16x8 b, f32x4 c) { return __builtin_amdgcn_mfma_f32_16x16x32_bf16(a, b, c, 0, 0, 0); }
; __device__ __forceinline__ float gelu_tanh_f(float x) {
;     const float u = 0.7978845608028654f * (x + 0.044715f * x * x * x);
;     const float t = 1.f - 2.f * __builtin_amdgcn_rcpf(1.f + __expf(2.f * u));
;     return 0.5f * x * (1.f + t);
; }
; __device__ __forceinline__ void ssm_out_unit(const Args& a, int unit) {
;     ...
;         for (int rk = 0; rk < 2; ++rk) af[rk] = *(const bf16x8*)(HC + ((size_t)(wave * 32 + rk * 16 + r16) * 32 + g) * 128 + kb * 32 + quad * 8);
; #pragma unroll
;         for (int nb = 0; nb < 4; ++nb) { const bf16x8 bf = *(const bf16x8*)(MCT + ((size_t)g * 1024 + (cb * 4 + nb) * 16 + r16) * 128 + kb * 32 + quad * 8);
;             acc[0][nb] = mfma16(af[0], bf, acc[0][nb]); acc[1][nb] = mfma16(af[1], bf, acc[1][nb]); }
;     }
; #pragma unroll
;     for (int rk = 0; rk < 2; ++rk)
; #pragma unroll
;         for (int nb = 0; nb < 4; ++nb)
; #pragma unroll
;             for (int i = 0; i < 4; ++i) { const int chunk = wave * 32 + rk * 16 + quad * 4 + i, t = chunk * 64 + cb * 4 + nb;
;                 YS[(size_t)t * 512 + g * 16 + r16] = (bf16_t)f2bf(gelu_tanh_f(acc[rk][nb][i])); }
	v_mfma_f32_16x16x32_bf16 v[28:31], v[104:107], v[112:115], v[28:31]
	v_mfma_f32_16x16x32_bf16 v[16:19], v[104:107], v[124:127], v[16:19]
	v_mfma_f32_16x16x32_bf16 v[12:15], v[108:111], v[112:115], v[12:15]
	v_mfma_f32_16x16x32_bf16 v[24:27], v[104:107], v[116:119], v[24:27]
	v_mfma_f32_16x16x32_bf16 v[4:7], v[108:111], v[120:123], v[4:7]
	v_mfma_f32_16x16x32_bf16 v[8:11], v[108:111], v[116:119], v[8:11]
	v_mfma_f32_16x16x32_bf16 v[20:23], v[104:107], v[120:123], v[20:23]
	v_mfma_f32_16x16x32_bf16 v[0:3], v[108:111], v[124:127], v[0:3]
	s_nop 7
	v_mul_f32_e32 v35, 0x3d372713, v28
	v_mul_f32_e32 v35, v28, v35
	v_fma_f32 v35, v28, v35, v28
	v_mul_f32_e32 v35, 0x3f4c422a, v35
	v_add_f32_e32 v35, v35, v35
	v_mul_f32_e32 v35, 0x3fb8aa3b, v35
	v_exp_f32_e32 v35, v35
	v_mul_f32_e32 v28, 0.5, v28
	v_lshl_add_u64 v[32:33], s[0:1], 0, v[136:137]
	v_lshl_or_b32 v34, v154, 8, v155
	v_add_f32_e32 v35, 1.0, v35
	v_rcp_f32_e32 v35, v35
	v_readlane_b32 s0, v251, 24
	v_readlane_b32 s1, v251, 22
	v_fma_f32 v35, v35, -2.0, 1.0
	v_add_f32_e32 v35, 1.0, v35
	v_mul_f32_e32 v28, v28, v35
	v_mul_f32_e32 v35, 0x3d372713, v29
	v_mul_f32_e32 v35, v29, v35
	v_fma_f32 v35, v29, v35, v29
	v_mul_f32_e32 v35, 0x3f4c422a, v35
	v_add_f32_e32 v35, v35, v35
	v_mul_f32_e32 v35, 0x3fb8aa3b, v35
	v_exp_f32_e32 v35, v35
	v_mul_f32_e32 v29, 0.5, v29
	v_or_b32_e32 v36, s0, v34
	v_ashrrev_i32_e32 v37, 31, v36
	v_add_f32_e32 v35, 1.0, v35
	v_rcp_f32_e32 v35, v35
	v_lshlrev_b64 v[36:37], 10, v[36:37]
	v_cvt_pk_bf16_f32 v28, v28, s0
	v_lshl_add_u64 v[36:37], v[32:33], 0, v[36:37]
	v_fma_f32 v35, v35, -2.0, 1.0
	v_add_f32_e32 v35, 1.0, v35
	v_mul_f32_e32 v29, v29, v35
	v_mul_f32_e32 v35, 0x3d372713, v30
	v_mul_f32_e32 v35, v30, v35
	v_fma_f32 v35, v30, v35, v30
	v_mul_f32_e32 v35, 0x3f4c422a, v35
	v_add_f32_e32 v35, v35, v35
	v_mul_f32_e32 v35, 0x3fb8aa3b, v35
	v_exp_f32_e32 v35, v35
	v_mul_f32_e32 v30, 0.5, v30
	global_store_short v[36:37], v28, off
	v_or_b32_e32 v28, 64, v34
	v_add_f32_e32 v35, 1.0, v35
	v_rcp_f32_e32 v35, v35
	v_or_b32_e32 v36, s0, v28
	v_ashrrev_i32_e32 v37, 31, v36
	v_lshlrev_b64 v[36:37], 10, v[36:37]
	v_fma_f32 v35, v35, -2.0, 1.0
	v_add_f32_e32 v35, 1.0, v35
	v_mul_f32_e32 v30, v30, v35
	v_mul_f32_e32 v35, 0x3d372713, v31
	v_mul_f32_e32 v35, v31, v35
	v_fma_f32 v35, v31, v35, v31
	v_mul_f32_e32 v35, 0x3f4c422a, v35
	v_add_f32_e32 v35, v35, v35
	v_mul_f32_e32 v35, 0x3fb8aa3b, v35
	v_exp_f32_e32 v35, v35
	v_cvt_pk_bf16_f32 v29, v29, s0
	v_lshl_add_u64 v[36:37], v[32:33], 0, v[36:37]
	global_store_short v[36:37], v29, off
	v_or_b32_e32 v29, 0x80, v34
	v_or_b32_e32 v36, s0, v29
	v_add_f32_e32 v35, 1.0, v35
	v_ashrrev_i32_e32 v37, 31, v36
	v_rcp_f32_e32 v35, v35
	v_lshlrev_b64 v[36:37], 10, v[36:37]
	v_cvt_pk_bf16_f32 v30, v30, s0
	v_lshl_add_u64 v[36:37], v[32:33], 0, v[36:37]
	global_store_short v[36:37], v30, off
	v_or_b32_e32 v30, 0xc0, v34
	v_or_b32_e32 v36, s0, v30
	v_fma_f32 v35, v35, -2.0, 1.0
	v_mul_f32_e32 v31, 0.5, v31
	v_add_f32_e32 v35, 1.0, v35
	v_ashrrev_i32_e32 v37, 31, v36
	v_mul_f32_e32 v31, v31, v35
	v_lshlrev_b64 v[36:37], 10, v[36:37]
	v_cvt_pk_bf16_f32 v31, v31, s0
	v_lshl_add_u64 v[36:37], v[32:33], 0, v[36:37]
	global_store_short v[36:37], v31, off
	v_mul_f32_e32 v31, 0x3d372713, v24
	v_mul_f32_e32 v31, v24, v31
	v_fma_f32 v31, v24, v31, v24
	v_mul_f32_e32 v31, 0x3f4c422a, v31
	v_add_f32_e32 v31, v31, v31
	v_mul_f32_e32 v31, 0x3fb8aa3b, v31
	v_exp_f32_e32 v31, v31
	v_mul_f32_e32 v24, 0.5, v24
	v_or_b32_e32 v36, s1, v34
	v_ashrrev_i32_e32 v37, 31, v36
	v_add_f32_e32 v31, 1.0, v31
	v_rcp_f32_e32 v31, v31
	v_lshlrev_b64 v[36:37], 10, v[36:37]
	v_lshl_add_u64 v[36:37], v[32:33], 0, v[36:37]
	v_fma_f32 v31, v31, -2.0, 1.0
	v_add_f32_e32 v31, 1.0, v31
	v_mul_f32_e32 v24, v24, v31
	v_mul_f32_e32 v31, 0x3d372713, v25
	v_mul_f32_e32 v31, v25, v31
	v_fma_f32 v31, v25, v31, v25
	v_mul_f32_e32 v31, 0x3f4c422a, v31
	v_add_f32_e32 v31, v31, v31
	v_mul_f32_e32 v31, 0x3fb8aa3b, v31
	v_exp_f32_e32 v31, v31
	v_cvt_pk_bf16_f32 v24, v24, s0
	v_mul_f32_e32 v25, 0.5, v25
	global_store_short v[36:37], v24, off
	v_add_f32_e32 v31, 1.0, v31
	v_rcp_f32_e32 v31, v31
	v_or_b32_e32 v24, s1, v28
	v_fma_f32 v31, v31, -2.0, 1.0
	v_add_f32_e32 v31, 1.0, v31
	v_mul_f32_e32 v25, v25, v31
	v_cvt_pk_bf16_f32 v31, v25, s0
	v_ashrrev_i32_e32 v25, 31, v24
	v_lshlrev_b64 v[24:25], 10, v[24:25]
	v_lshl_add_u64 v[24:25], v[32:33], 0, v[24:25]
	global_store_short v[24:25], v31, off
	v_mul_f32_e32 v25, 0x3d372713, v26
	v_mul_f32_e32 v25, v26, v25
	v_fma_f32 v25, v26, v25, v26
	v_mul_f32_e32 v25, 0x3f4c422a, v25
	v_add_f32_e32 v25, v25, v25
	v_mul_f32_e32 v25, 0x3fb8aa3b, v25
	v_exp_f32_e32 v25, v25
	v_mul_f32_e32 v26, 0.5, v26
	v_or_b32_e32 v24, s1, v29
	v_add_f32_e32 v25, 1.0, v25
	v_rcp_f32_e32 v25, v25
	s_nop 0
	v_fma_f32 v25, v25, -2.0, 1.0
	v_add_f32_e32 v25, 1.0, v25
	v_mul_f32_e32 v25, v26, v25
	v_cvt_pk_bf16_f32 v26, v25, s0
	v_ashrrev_i32_e32 v25, 31, v24
	v_lshlrev_b64 v[24:25], 10, v[24:25]
	v_lshl_add_u64 v[24:25], v[32:33], 0, v[24:25]
	global_store_short v[24:25], v26, off
	v_mul_f32_e32 v25, 0x3d372713, v27
	v_mul_f32_e32 v25, v27, v25
	v_fma_f32 v25, v27, v25, v27
	v_mul_f32_e32 v25, 0x3f4c422a, v25
	v_add_f32_e32 v25, v25, v25
	v_mul_f32_e32 v25, 0x3fb8aa3b, v25
	v_exp_f32_e32 v25, v25
	v_mul_f32_e32 v26, 0.5, v27
	v_or_b32_e32 v24, s1, v30
	v_add_f32_e32 v25, 1.0, v25
	v_rcp_f32_e32 v25, v25
	s_nop 0
	v_fma_f32 v25, v25, -2.0, 1.0
	v_add_f32_e32 v25, 1.0, v25
	v_mul_f32_e32 v25, v26, v25
	v_cvt_pk_bf16_f32 v26, v25, s0
	v_ashrrev_i32_e32 v25, 31, v24
	v_lshlrev_b64 v[24:25], 10, v[24:25]
	v_lshl_add_u64 v[24:25], v[32:33], 0, v[24:25]
	global_store_short v[24:25], v26, off
; __device__ __forceinline__ unsigned f2bf(float f) { return pk2(f, 0.f) & 0xffffu; }
; __device__ __forceinline__ float gelu_tanh_f(float x) {
;     const float u = 0.7978845608028654f * (x + 0.044715f * x * x * x);
;     const float t = 1.f - 2.f * __builtin_amdgcn_rcpf(1.f + __expf(2.f * u));
;     return 0.5f * x * (1.f + t);
; }
; __device__ __forceinline__ void ssm_out_unit(const Args& a, int unit) {
;     ...
; #pragma unroll
;     for (int rk = 0; rk < 2; ++rk)
; #pragma unroll
;         for (int nb = 0; nb < 4; ++nb)
; #pragma unroll
;             for (int i = 0; i < 4; ++i) { const int chunk = wave * 32 + rk * 16 + quad * 4 + i, t = chunk * 64 + cb * 4 + nb;
;                 YS[(size_t)t * 512 + g * 16 + r16] = (bf16_t)f2bf(gelu_tanh_f(acc[rk][nb][i])); }
	v_mul_f32_e32 v25, 0x3d372713, v20
	v_mul_f32_e32 v25, v20, v25
	v_fma_f32 v25, v20, v25, v20
	v_mul_f32_e32 v25, 0x3f4c422a, v25
	v_add_f32_e32 v25, v25, v25
	v_mul_f32_e32 v25, 0x3fb8aa3b, v25
	v_exp_f32_e32 v25, v25
	v_or_b32_e32 v24, s4, v34
	v_mul_f32_e32 v20, 0.5, v20
	v_add_f32_e32 v25, 1.0, v25
	v_rcp_f32_e32 v25, v25
	s_nop 0
	v_fma_f32 v25, v25, -2.0, 1.0
	v_add_f32_e32 v25, 1.0, v25
	v_mul_f32_e32 v20, v20, v25
	v_ashrrev_i32_e32 v25, 31, v24
	v_lshlrev_b64 v[24:25], 10, v[24:25]
	v_cvt_pk_bf16_f32 v20, v20, s0
	v_lshl_add_u64 v[24:25], v[32:33], 0, v[24:25]
	global_store_short v[24:25], v20, off
	v_mul_f32_e32 v24, 0x3d372713, v21
	v_mul_f32_e32 v24, v21, v24
	v_fma_f32 v24, v21, v24, v21
	v_mul_f32_e32 v24, 0x3f4c422a, v24
	v_add_f32_e32 v24, v24, v24
	v_mul_f32_e32 v24, 0x3fb8aa3b, v24
	v_exp_f32_e32 v24, v24
	v_mul_f32_e32 v21, 0.5, v21
	v_or_b32_e32 v20, s4, v28
	v_add_f32_e32 v24, 1.0, v24
	v_rcp_f32_e32 v24, v24
	s_nop 0
	v_fma_f32 v24, v24, -2.0, 1.0
	v_add_f32_e32 v24, 1.0, v24
	v_mul_f32_e32 v21, v21, v24
	v_cvt_pk_bf16_f32 v24, v21, s0
	v_ashrrev_i32_e32 v21, 31, v20
	v_lshlrev_b64 v[20:21], 10, v[20:21]
	v_lshl_add_u64 v[20:21], v[32:33], 0, v[20:21]
	global_store_short v[20:21], v24, off
	v_mul_f32_e32 v21, 0x3d372713, v22
	v_mul_f32_e32 v21, v22, v21
	v_fma_f32 v21, v22, v21, v22
	v_mul_f32_e32 v21, 0x3f4c422a, v21
	v_add_f32_e32 v21, v21, v21
	v_mul_f32_e32 v21, 0x3fb8aa3b, v21
	v_exp_f32_e32 v21, v21
	v_mul_f32_e32 v22, 0.5, v22
	v_or_b32_e32 v20, s4, v29
	v_add_f32_e32 v21, 1.0, v21
	v_rcp_f32_e32 v21, v21
	s_nop 0
	v_fma_f32 v21, v21, -2.0, 1.0
	v_add_f32_e32 v21, 1.0, v21
	v_mul_f32_e32 v21, v22, v21
	v_cvt_pk_bf16_f32 v22, v21, s0
	v_ashrrev_i32_e32 v21, 31, v20
	v_lshlrev_b64 v[20:21], 10, v[20:21]
	v_lshl_add_u64 v[20:21], v[32:33], 0, v[20:21]
	global_store_short v[20:21], v22, off
	v_mul_f32_e32 v21, 0x3d372713, v23
	v_mul_f32_e32 v21, v23, v21
	v_fma_f32 v21, v23, v21, v23
	v_mul_f32_e32 v21, 0x3f4c422a, v21
	v_add_f32_e32 v21, v21, v21
	v_mul_f32_e32 v21, 0x3fb8aa3b, v21
	v_exp_f32_e32 v21, v21
	v_mul_f32_e32 v22, 0.5, v23
	v_or_b32_e32 v20, s4, v30
	v_add_f32_e32 v21, 1.0, v21
	v_rcp_f32_e32 v21, v21
	s_nop 0
	v_fma_f32 v21, v21, -2.0, 1.0
	v_add_f32_e32 v21, 1.0, v21
	v_mul_f32_e32 v21, v22, v21
	v_cvt_pk_bf16_f32 v22, v21, s0
	v_ashrrev_i32_e32 v21, 31, v20
	v_lshlrev_b64 v[20:21], 10, v[20:21]
	v_lshl_add_u64 v[20:21], v[32:33], 0, v[20:21]
	global_store_short v[20:21], v22, off
	v_mul_f32_e32 v21, 0x3d372713, v16
	v_mul_f32_e32 v21, v16, v21
	v_fma_f32 v21, v16, v21, v16
	v_mul_f32_e32 v21, 0x3f4c422a, v21
	v_add_f32_e32 v21, v21, v21
	v_mul_f32_e32 v21, 0x3fb8aa3b, v21
	v_exp_f32_e32 v21, v21
	v_or_b32_e32 v20, s8, v34
	v_mul_f32_e32 v16, 0.5, v16
	v_add_f32_e32 v21, 1.0, v21
	v_rcp_f32_e32 v21, v21
	s_nop 0
	v_fma_f32 v21, v21, -2.0, 1.0
	v_add_f32_e32 v21, 1.0, v21
	v_mul_f32_e32 v16, v16, v21
	v_ashrrev_i32_e32 v21, 31, v20
	v_lshlrev_b64 v[20:21], 10, v[20:21]
	v_cvt_pk_bf16_f32 v16, v16, s0
	v_lshl_add_u64 v[20:21], v[32:33], 0, v[20:21]
	global_store_short v[20:21], v16, off
	v_mul_f32_e32 v20, 0x3d372713, v17
	v_mul_f32_e32 v20, v17, v20
	v_fma_f32 v20, v17, v20, v17
	v_mul_f32_e32 v20, 0x3f4c422a, v20
	v_add_f32_e32 v20, v20, v20
	v_mul_f32_e32 v20, 0x3fb8aa3b, v20
	v_exp_f32_e32 v20, v20
	v_mul_f32_e32 v17, 0.5, v17
	v_or_b32_e32 v16, s8, v28
	v_add_f32_e32 v20, 1.0, v20
	v_rcp_f32_e32 v20, v20
	s_nop 0
	v_fma_f32 v20, v20, -2.0, 1.0
	v_add_f32_e32 v20, 1.0, v20
	v_mul_f32_e32 v17, v17, v20
	v_cvt_pk_bf16_f32 v20, v17, s0
	v_ashrrev_i32_e32 v17, 31, v16
	v_lshlrev_b64 v[16:17], 10, v[16:17]
	v_lshl_add_u64 v[16:17], v[32:33], 0, v[16:17]
	global_store_short v[16:17], v20, off
	v_mul_f32_e32 v17, 0x3d372713, v18
	v_mul_f32_e32 v17, v18, v17
	v_fma_f32 v17, v18, v17, v18
	v_mul_f32_e32 v17, 0x3f4c422a, v17
	v_add_f32_e32 v17, v17, v17
	v_mul_f32_e32 v17, 0x3fb8aa3b, v17
	v_exp_f32_e32 v17, v17
	v_mul_f32_e32 v18, 0.5, v18
	v_or_b32_e32 v16, s8, v29
	v_add_f32_e32 v17, 1.0, v17
	v_rcp_f32_e32 v17, v17
	s_nop 0
	v_fma_f32 v17, v17, -2.0, 1.0
	v_add_f32_e32 v17, 1.0, v17
	v_mul_f32_e32 v17, v18, v17
	v_cvt_pk_bf16_f32 v18, v17, s0
	v_ashrrev_i32_e32 v17, 31, v16
	v_lshlrev_b64 v[16:17], 10, v[16:17]
	v_lshl_add_u64 v[16:17], v[32:33], 0, v[16:17]
	global_store_short v[16:17], v18, off
	v_mul_f32_e32 v17, 0x3d372713, v19
	v_mul_f32_e32 v17, v19, v17
	v_fma_f32 v17, v19, v17, v19
	v_mul_f32_e32 v17, 0x3f4c422a, v17
	v_add_f32_e32 v17, v17, v17
	v_mul_f32_e32 v17, 0x3fb8aa3b, v17
	v_exp_f32_e32 v17, v17
	v_mul_f32_e32 v18, 0.5, v19
	v_or_b32_e32 v16, s8, v30
	v_add_f32_e32 v17, 1.0, v17
	v_rcp_f32_e32 v17, v17
	s_nop 0
	v_fma_f32 v17, v17, -2.0, 1.0
	v_add_f32_e32 v17, 1.0, v17
	v_mul_f32_e32 v17, v18, v17
	v_cvt_pk_bf16_f32 v18, v17, s0
	v_ashrrev_i32_e32 v17, 31, v16
	v_lshlrev_b64 v[16:17], 10, v[16:17]
	v_lshl_add_u64 v[16:17], v[32:33], 0, v[16:17]
	global_store_short v[16:17], v18, off
	v_mul_f32_e32 v17, 0x3d372713, v12
	v_mul_f32_e32 v17, v12, v17
	v_fma_f32 v17, v12, v17, v12
	v_mul_f32_e32 v17, 0x3f4c422a, v17
	v_add_f32_e32 v17, v17, v17
	v_mul_f32_e32 v17, 0x3fb8aa3b, v17
	v_exp_f32_e32 v17, v17
	v_mul_f32_e32 v12, 0.5, v12
	v_or_b32_e32 v16, 0x400, v34
	v_or_b32_e32 v18, s0, v16
	v_add_f32_e32 v17, 1.0, v17
	v_rcp_f32_e32 v17, v17
	v_ashrrev_i32_e32 v19, 31, v18
	v_lshlrev_b64 v[18:19], 10, v[18:19]
	v_lshl_add_u64 v[18:19], v[32:33], 0, v[18:19]
	v_fma_f32 v17, v17, -2.0, 1.0
	v_add_f32_e32 v17, 1.0, v17
	v_mul_f32_e32 v12, v12, v17
	v_mul_f32_e32 v17, 0x3d372713, v13
	v_mul_f32_e32 v17, v13, v17
	v_fma_f32 v17, v13, v17, v13
	v_mul_f32_e32 v17, 0x3f4c422a, v17
	v_add_f32_e32 v17, v17, v17
; __device__ __forceinline__ unsigned f2bf(float f) { return pk2(f, 0.f) & 0xffffu; }
; __device__ __forceinline__ float gelu_tanh_f(float x) {
;     const float u = 0.7978845608028654f * (x + 0.044715f * x * x * x);
;     const float t = 1.f - 2.f * __builtin_amdgcn_rcpf(1.f + __expf(2.f * u));
;     return 0.5f * x * (1.f + t);
; }
; __device__ __forceinline__ void ssm_out_unit(const Args& a, int unit) {
;     ...
; #pragma unroll
;     for (int rk = 0; rk < 2; ++rk)
; #pragma unroll
;         for (int nb = 0; nb < 4; ++nb)
; #pragma unroll
;             for (int i = 0; i < 4; ++i) { const int chunk = wave * 32 + rk * 16 + quad * 4 + i, t = chunk * 64 + cb * 4 + nb;
;                 YS[(size_t)t * 512 + g * 16 + r16] = (bf16_t)f2bf(gelu_tanh_f(acc[rk][nb][i])); }
	v_mul_f32_e32 v17, 0x3fb8aa3b, v17
	v_exp_f32_e32 v17, v17
	v_mul_f32_e32 v13, 0.5, v13
	v_cvt_pk_bf16_f32 v12, v12, s0
	global_store_short v[18:19], v12, off
	v_add_f32_e32 v17, 1.0, v17
	v_rcp_f32_e32 v17, v17
	v_or_b32_e32 v12, 0x440, v34
	v_or_b32_e32 v18, s0, v12
	v_ashrrev_i32_e32 v19, 31, v18
	v_fma_f32 v17, v17, -2.0, 1.0
	v_add_f32_e32 v17, 1.0, v17
	v_mul_f32_e32 v13, v13, v17
	v_mul_f32_e32 v17, 0x3d372713, v14
	v_mul_f32_e32 v17, v14, v17
	v_fma_f32 v17, v14, v17, v14
	v_mul_f32_e32 v17, 0x3f4c422a, v17
	v_add_f32_e32 v17, v17, v17
	v_mul_f32_e32 v17, 0x3fb8aa3b, v17
	v_exp_f32_e32 v17, v17
	v_mul_f32_e32 v14, 0.5, v14
	v_lshlrev_b64 v[18:19], 10, v[18:19]
	v_cvt_pk_bf16_f32 v13, v13, s0
	v_add_f32_e32 v17, 1.0, v17
	v_rcp_f32_e32 v17, v17
	v_lshl_add_u64 v[18:19], v[32:33], 0, v[18:19]
	global_store_short v[18:19], v13, off
	v_or_b32_e32 v13, 0x480, v34
	v_fma_f32 v17, v17, -2.0, 1.0
	v_add_f32_e32 v17, 1.0, v17
	v_mul_f32_e32 v14, v14, v17
	v_mul_f32_e32 v17, 0x3d372713, v15
	v_mul_f32_e32 v17, v15, v17
	v_fma_f32 v17, v15, v17, v15
	v_mul_f32_e32 v17, 0x3f4c422a, v17
	v_add_f32_e32 v17, v17, v17
	v_mul_f32_e32 v17, 0x3fb8aa3b, v17
	v_exp_f32_e32 v17, v17
	v_or_b32_e32 v18, s0, v13
	v_ashrrev_i32_e32 v19, 31, v18
	v_lshlrev_b64 v[18:19], 10, v[18:19]
	v_add_f32_e32 v17, 1.0, v17
	v_rcp_f32_e32 v17, v17
	v_cvt_pk_bf16_f32 v14, v14, s0
	v_lshl_add_u64 v[18:19], v[32:33], 0, v[18:19]
	global_store_short v[18:19], v14, off
	v_or_b32_e32 v14, 0x4c0, v34
	v_or_b32_e32 v18, s0, v14
	v_fma_f32 v17, v17, -2.0, 1.0
	v_mul_f32_e32 v15, 0.5, v15
	v_add_f32_e32 v17, 1.0, v17
	v_ashrrev_i32_e32 v19, 31, v18
	v_mul_f32_e32 v15, v15, v17
	v_lshlrev_b64 v[18:19], 10, v[18:19]
	v_cvt_pk_bf16_f32 v15, v15, s0
	v_lshl_add_u64 v[18:19], v[32:33], 0, v[18:19]
	global_store_short v[18:19], v15, off
	v_mul_f32_e32 v15, 0x3d372713, v8
	v_mul_f32_e32 v15, v8, v15
	v_fma_f32 v15, v8, v15, v8
	v_mul_f32_e32 v15, 0x3f4c422a, v15
	v_add_f32_e32 v15, v15, v15
	v_mul_f32_e32 v15, 0x3fb8aa3b, v15
	v_exp_f32_e32 v15, v15
	v_mul_f32_e32 v8, 0.5, v8
	v_or_b32_e32 v18, s1, v16
	v_ashrrev_i32_e32 v19, 31, v18
	v_add_f32_e32 v15, 1.0, v15
	v_rcp_f32_e32 v15, v15
	v_lshlrev_b64 v[18:19], 10, v[18:19]
	v_lshl_add_u64 v[18:19], v[32:33], 0, v[18:19]
	v_fma_f32 v15, v15, -2.0, 1.0
	v_add_f32_e32 v15, 1.0, v15
	v_mul_f32_e32 v8, v8, v15
	v_mul_f32_e32 v15, 0x3d372713, v9
	v_mul_f32_e32 v15, v9, v15
	v_fma_f32 v15, v9, v15, v9
	v_mul_f32_e32 v15, 0x3f4c422a, v15
	v_add_f32_e32 v15, v15, v15
	v_mul_f32_e32 v15, 0x3fb8aa3b, v15
	v_exp_f32_e32 v15, v15
	v_cvt_pk_bf16_f32 v8, v8, s0
	v_mul_f32_e32 v9, 0.5, v9
	global_store_short v[18:19], v8, off
	v_add_f32_e32 v15, 1.0, v15
	v_rcp_f32_e32 v15, v15
	v_or_b32_e32 v8, s1, v12
	v_fma_f32 v15, v15, -2.0, 1.0
	v_add_f32_e32 v15, 1.0, v15
	v_mul_f32_e32 v9, v9, v15
	v_cvt_pk_bf16_f32 v15, v9, s0
	v_ashrrev_i32_e32 v9, 31, v8
	v_lshlrev_b64 v[8:9], 10, v[8:9]
	v_lshl_add_u64 v[8:9], v[32:33], 0, v[8:9]
	global_store_short v[8:9], v15, off
	v_mul_f32_e32 v9, 0x3d372713, v10
	v_mul_f32_e32 v9, v10, v9
	v_fma_f32 v9, v10, v9, v10
	v_mul_f32_e32 v9, 0x3f4c422a, v9
	v_add_f32_e32 v9, v9, v9
	v_mul_f32_e32 v9, 0x3fb8aa3b, v9
	v_exp_f32_e32 v9, v9
	v_mul_f32_e32 v10, 0.5, v10
	v_or_b32_e32 v8, s1, v13
	v_add_f32_e32 v9, 1.0, v9
	v_rcp_f32_e32 v9, v9
	s_nop 0
	v_fma_f32 v9, v9, -2.0, 1.0
	v_add_f32_e32 v9, 1.0, v9
	v_mul_f32_e32 v9, v10, v9
	v_cvt_pk_bf16_f32 v10, v9, s0
	v_ashrrev_i32_e32 v9, 31, v8
	v_lshlrev_b64 v[8:9], 10, v[8:9]
	v_lshl_add_u64 v[8:9], v[32:33], 0, v[8:9]
	global_store_short v[8:9], v10, off
	v_mul_f32_e32 v9, 0x3d372713, v11
	v_mul_f32_e32 v9, v11, v9
	v_fma_f32 v9, v11, v9, v11
	v_mul_f32_e32 v9, 0x3f4c422a, v9
	v_add_f32_e32 v9, v9, v9
	v_mul_f32_e32 v9, 0x3fb8aa3b, v9
	v_exp_f32_e32 v9, v9
	v_mul_f32_e32 v10, 0.5, v11
	v_or_b32_e32 v8, s1, v14
	v_add_f32_e32 v9, 1.0, v9
	v_rcp_f32_e32 v9, v9
	s_nop 0
	v_fma_f32 v9, v9, -2.0, 1.0
	v_add_f32_e32 v9, 1.0, v9
	v_mul_f32_e32 v9, v10, v9
	v_cvt_pk_bf16_f32 v10, v9, s0
	v_ashrrev_i32_e32 v9, 31, v8
	v_lshlrev_b64 v[8:9], 10, v[8:9]
	v_lshl_add_u64 v[8:9], v[32:33], 0, v[8:9]
	global_store_short v[8:9], v10, off
	v_mul_f32_e32 v9, 0x3d372713, v4
	v_mul_f32_e32 v9, v4, v9
	v_fma_f32 v9, v4, v9, v4
	v_mul_f32_e32 v9, 0x3f4c422a, v9
	v_add_f32_e32 v9, v9, v9
	v_mul_f32_e32 v9, 0x3fb8aa3b, v9
	v_exp_f32_e32 v9, v9
	v_or_b32_e32 v8, s4, v16
	v_mul_f32_e32 v4, 0.5, v4
	v_add_f32_e32 v9, 1.0, v9
	v_rcp_f32_e32 v9, v9
	s_nop 0
	v_fma_f32 v9, v9, -2.0, 1.0
	v_add_f32_e32 v9, 1.0, v9
	v_mul_f32_e32 v4, v4, v9
	v_ashrrev_i32_e32 v9, 31, v8
	v_lshlrev_b64 v[8:9], 10, v[8:9]
	v_cvt_pk_bf16_f32 v4, v4, s0
	v_lshl_add_u64 v[8:9], v[32:33], 0, v[8:9]
	global_store_short v[8:9], v4, off
	v_mul_f32_e32 v8, 0x3d372713, v5
	v_mul_f32_e32 v8, v5, v8
	v_fma_f32 v8, v5, v8, v5
	v_mul_f32_e32 v8, 0x3f4c422a, v8
	v_add_f32_e32 v8, v8, v8
	v_mul_f32_e32 v8, 0x3fb8aa3b, v8
	v_exp_f32_e32 v8, v8
	v_mul_f32_e32 v5, 0.5, v5
	v_or_b32_e32 v4, s4, v12
	v_add_f32_e32 v8, 1.0, v8
	v_rcp_f32_e32 v8, v8
	s_nop 0
	v_fma_f32 v8, v8, -2.0, 1.0
	v_add_f32_e32 v8, 1.0, v8
	v_mul_f32_e32 v5, v5, v8
	v_cvt_pk_bf16_f32 v8, v5, s0
	v_ashrrev_i32_e32 v5, 31, v4
; __device__ __forceinline__ unsigned f2bf(float f) { return pk2(f, 0.f) & 0xffffu; }
; __device__ __forceinline__ void ssm_out_unit(const Args& a, int unit) {
;     ...
;     f32x4 acc[2][4];
; #pragma unroll
;     for (int i = 0; i < 2; ++i)
; #pragma unroll
;         for (int k = 0; k < 4; ++k) acc[i][k] = (f32x4){0.f, 0.f, 0.f, 0.f};
;     const int kbn = cb * 2 + 2;
;     const bf16x8 zero8 = (bf16x8){0, 0, 0, 0, 0, 0, 0, 0};
;     for (int kb0 = 0; kb0 < kbn; kb0 += 4) {
;         bf16x8 af[4][2], bf[4][4];
; #pragma unroll
;         for (int u = 0; u < 4; ++u) {
;             const int kb = kb0 + u, jp = kb * 2 + jo; const bool on = kb < kbn;
; #pragma unroll
;             for (int rk = 0; rk < 2; ++rk) af[u][rk] = on ? *(const bf16x8*)(XS + ((size_t)g * T + (wave * 32 + rk * 16 + r16) * 64 + jp) * 16 + ch) : zero8;
; #pragma unroll
;     ...
; #pragma unroll
;     for (int rk = 0; rk < 2; ++rk)
; #pragma unroll
;         for (int nb = 0; nb < 4; ++nb)
; #pragma unroll
;             for (int i = 0; i < 4; ++i) { const int chunk = wave * 32 + rk * 16 + quad * 4 + i, t = chunk * 64 + cb * 4 + nb;
;                 YS[(size_t)t * 512 + g * 16 + r16] = (bf16_t)f2bf(gelu_tanh_f(acc[rk][nb][i])); }
	v_lshlrev_b64 v[4:5], 10, v[4:5]
	v_lshl_add_u64 v[4:5], v[32:33], 0, v[4:5]
	global_store_short v[4:5], v8, off
	v_mul_f32_e32 v5, 0x3d372713, v6
	v_mul_f32_e32 v5, v6, v5
	v_fma_f32 v5, v6, v5, v6
	v_mul_f32_e32 v5, 0x3f4c422a, v5
	v_add_f32_e32 v5, v5, v5
	v_mul_f32_e32 v5, 0x3fb8aa3b, v5
	v_exp_f32_e32 v5, v5
	v_mul_f32_e32 v6, 0.5, v6
	v_or_b32_e32 v4, s4, v13
	v_add_f32_e32 v5, 1.0, v5
	v_rcp_f32_e32 v5, v5
	s_nop 0
	v_fma_f32 v5, v5, -2.0, 1.0
	v_add_f32_e32 v5, 1.0, v5
	v_mul_f32_e32 v5, v6, v5
	v_cvt_pk_bf16_f32 v6, v5, s0
	v_ashrrev_i32_e32 v5, 31, v4
	v_lshlrev_b64 v[4:5], 10, v[4:5]
	v_lshl_add_u64 v[4:5], v[32:33], 0, v[4:5]
	global_store_short v[4:5], v6, off
	v_mul_f32_e32 v5, 0x3d372713, v7
	v_mul_f32_e32 v5, v7, v5
	v_fma_f32 v5, v7, v5, v7
	v_mul_f32_e32 v5, 0x3f4c422a, v5
	v_add_f32_e32 v5, v5, v5
	v_mul_f32_e32 v5, 0x3fb8aa3b, v5
	v_exp_f32_e32 v5, v5
	v_mul_f32_e32 v6, 0.5, v7
	v_or_b32_e32 v4, s4, v14
	s_mov_b32 s4, 0
	v_add_f32_e32 v5, 1.0, v5
	v_rcp_f32_e32 v5, v5
	s_nop 0
	v_fma_f32 v5, v5, -2.0, 1.0
	v_add_f32_e32 v5, 1.0, v5
	v_mul_f32_e32 v5, v6, v5
	v_cvt_pk_bf16_f32 v6, v5, s0
	v_ashrrev_i32_e32 v5, 31, v4
	v_lshlrev_b64 v[4:5], 10, v[4:5]
	v_lshl_add_u64 v[4:5], v[32:33], 0, v[4:5]
	global_store_short v[4:5], v6, off
	v_mul_f32_e32 v5, 0x3d372713, v0
	v_mul_f32_e32 v5, v0, v5
	v_fma_f32 v5, v0, v5, v0
	v_mul_f32_e32 v5, 0x3f4c422a, v5
	v_add_f32_e32 v5, v5, v5
	v_mul_f32_e32 v5, 0x3fb8aa3b, v5
	v_exp_f32_e32 v5, v5
	v_or_b32_e32 v4, s8, v16
	v_mul_f32_e32 v0, 0.5, v0
	v_mov_b32_e32 v16, 0
	v_add_f32_e32 v5, 1.0, v5
	v_rcp_f32_e32 v5, v5
	v_mov_b32_e32 v17, v16
	v_mov_b32_e32 v18, v16
	v_mov_b32_e32 v19, v16
	v_fma_f32 v5, v5, -2.0, 1.0
	v_add_f32_e32 v5, 1.0, v5
	v_mul_f32_e32 v0, v0, v5
	v_ashrrev_i32_e32 v5, 31, v4
	v_lshlrev_b64 v[4:5], 10, v[4:5]
	v_cvt_pk_bf16_f32 v0, v0, s0
	v_lshl_add_u64 v[4:5], v[32:33], 0, v[4:5]
	global_store_short v[4:5], v0, off
	v_mul_f32_e32 v4, 0x3d372713, v1
	v_mul_f32_e32 v4, v1, v4
	v_fma_f32 v4, v1, v4, v1
	v_mul_f32_e32 v4, 0x3f4c422a, v4
	v_add_f32_e32 v4, v4, v4
	v_mul_f32_e32 v4, 0x3fb8aa3b, v4
	v_exp_f32_e32 v4, v4
	v_mul_f32_e32 v1, 0.5, v1
	v_or_b32_e32 v0, s8, v12
	v_mov_b32_e32 v5, v16
	v_add_f32_e32 v4, 1.0, v4
	v_rcp_f32_e32 v4, v4
	v_mov_b32_e32 v6, v16
	v_mov_b32_e32 v7, v16
	v_mov_b32_e32 v12, v16
	v_fma_f32 v4, v4, -2.0, 1.0
	v_add_f32_e32 v4, 1.0, v4
	v_mul_f32_e32 v1, v1, v4
	v_cvt_pk_bf16_f32 v4, v1, s0
	v_ashrrev_i32_e32 v1, 31, v0
	v_lshlrev_b64 v[0:1], 10, v[0:1]
	v_lshl_add_u64 v[0:1], v[32:33], 0, v[0:1]
	global_store_short v[0:1], v4, off
	v_mul_f32_e32 v1, 0x3d372713, v2
	v_mul_f32_e32 v1, v2, v1
	v_fma_f32 v1, v2, v1, v2
	v_mul_f32_e32 v1, 0x3f4c422a, v1
	v_add_f32_e32 v1, v1, v1
	v_mul_f32_e32 v1, 0x3fb8aa3b, v1
	v_exp_f32_e32 v1, v1
	v_mul_f32_e32 v2, 0.5, v2
	v_or_b32_e32 v0, s8, v13
	v_mov_b32_e32 v4, v16
	v_add_f32_e32 v1, 1.0, v1
	v_rcp_f32_e32 v1, v1
	v_mov_b32_e32 v13, v16
	v_mov_b32_e32 v15, v16
	v_mov_b32_e32 v28, v16
	v_fma_f32 v1, v1, -2.0, 1.0
	v_add_f32_e32 v1, 1.0, v1
	v_mul_f32_e32 v1, v2, v1
	v_cvt_pk_bf16_f32 v2, v1, s0
	v_ashrrev_i32_e32 v1, 31, v0
	v_lshlrev_b64 v[0:1], 10, v[0:1]
	v_lshl_add_u64 v[0:1], v[32:33], 0, v[0:1]
	global_store_short v[0:1], v2, off
	v_mul_f32_e32 v1, 0x3d372713, v3
	v_mul_f32_e32 v1, v3, v1
	v_fma_f32 v1, v3, v1, v3
	v_mul_f32_e32 v1, 0x3f4c422a, v1
	v_add_f32_e32 v1, v1, v1
	v_mul_f32_e32 v1, 0x3fb8aa3b, v1
	v_exp_f32_e32 v1, v1
	v_mul_f32_e32 v2, 0.5, v3
	v_or_b32_e32 v0, s8, v14
	v_mov_b32_e32 v14, v16
	v_add_f32_e32 v1, 1.0, v1
	v_rcp_f32_e32 v1, v1
	v_mov_b32_e32 v29, v16
	v_mov_b32_e32 v30, v16
	v_mov_b32_e32 v31, v16
	v_fma_f32 v1, v1, -2.0, 1.0
	v_add_f32_e32 v1, 1.0, v1
	v_mul_f32_e32 v1, v2, v1
	v_cvt_pk_bf16_f32 v2, v1, s0
	v_ashrrev_i32_e32 v1, 31, v0
	v_lshlrev_b64 v[0:1], 10, v[0:1]
	v_lshl_add_u64 v[0:1], v[32:33], 0, v[0:1]
	global_store_short v[0:1], v2, off
	v_mov_b32_e32 v2, v174
	v_readlane_b32 s0, v251, 3
	v_ashrrev_i32_e32 v157, 6, v2
	v_and_b32_e32 v156, 15, v2
	v_lshrrev_b32_e32 v0, 4, v2
	v_lshlrev_b32_e32 v136, 5, v156
	v_readlane_b32 s1, v251, 4
	v_lshlrev_b32_e32 v155, 11, v157
	v_bfe_u32 v154, v2, 4, 2
	v_bfe_u32 v3, v0, 1, 1
	v_lshl_add_u64 v[0:1], s[0:1], 0, v[136:137]
	v_and_b32_e32 v136, 16, v2
	v_lshl_or_b32 v2, v156, 6, v155
	v_lshl_add_u64 v[128:129], v[0:1], 0, v[136:137]
	v_readlane_b32 s0, v251, 39
	v_ashrrev_i32_e32 v1, 31, v2
	v_or_b32_e32 v0, v2, v3
	v_sub_u32_e32 v158, s0, v3
	v_lshlrev_b64 v[0:1], 5, v[0:1]
	v_readlane_b32 s0, v253, 53
	v_or_b32_e32 v0, v0, v136
	v_readlane_b32 s1, v253, 54
	v_mov_b32_e32 v20, v16
	v_mov_b32_e32 v21, v16
	v_lshl_add_u64 v[130:131], s[0:1], 0, v[0:1]
	v_or_b32_e32 v0, 0x400, v2
	v_ashrrev_i32_e32 v1, 31, v0
	v_or_b32_e32 v0, v0, v3
	v_lshlrev_b64 v[0:1], 5, v[0:1]
	v_or_b32_e32 v0, v0, v136
	v_lshl_add_u64 v[132:133], s[0:1], 0, v[0:1]
	v_mov_b32_e32 v0, v16
	v_mov_b32_e32 v1, v16
	v_mov_b32_e32 v2, v16
	v_mov_b32_e32 v3, v16
	v_mov_b32_e32 v22, v16
	v_mov_b32_e32 v23, v16
	v_mov_b32_e32 v8, v16
	v_mov_b32_e32 v9, v16
	v_mov_b32_e32 v10, v16
	v_mov_b32_e32 v11, v16
	v_mov_b32_e32 v24, v16
	v_mov_b32_e32 v25, v16
	v_mov_b32_e32 v26, v16
	v_mov_b32_e32 v27, v16
	s_branch .LBB0_273

; __device__ __forceinline__ f32x4 mfma16(bf16x8 a, bf16x8 b, f32x4 c) { return __builtin_amdgcn_mfma_f32_16x16x32_bf16(a, b, c, 0, 0, 0); }
; __device__ __forceinline__ void ssm_out_unit(const Args& a, int unit) {
;     ...
; #pragma unroll
;     for (int kb = 0; kb < 4; ++kb) {
;         bf16x8 af[2];
; #pragma unroll
;         for (int rk = 0; rk < 2; ++rk) af[rk] = *(const bf16x8*)(HC + ((size_t)(wave * 32 + rk * 16 + r16) * 32 + g) * 128 + kb * 32 + quad * 8);
; #pragma unroll
;         for (int nb = 0; nb < 4; ++nb) { const bf16x8 bf = *(const bf16x8*)(MCT + ((size_t)g * 1024 + (cb * 4 + nb) * 16 + r16) * 128 + kb * 32 + quad * 8);
;             acc[0][nb] = mfma16(af[0], bf, acc[0][nb]); acc[1][nb] = mfma16(af[1], bf, acc[1][nb]); }
;     }
.LBB0_315:
	v_readlane_b32 s0, v251, 27
	v_readlane_b32 s1, v251, 28
	v_lshlrev_b32_e32 v136, 4, v154
	v_lshl_or_b32 v210, v157, 5, v156
	v_ashrrev_i32_e32 v211, 31, v210
	v_lshl_add_u64 v[212:213], s[0:1], 0, v[136:137]
	v_lshlrev_b64 v[214:215], 13, v[210:211]
	v_lshl_add_u64 v[214:215], v[212:213], 0, v[214:215]
	v_or_b32_e32 v210, 16, v210
	v_ashrrev_i32_e32 v211, 31, v210
	v_lshlrev_b64 v[216:217], 13, v[210:211]
	v_lshl_add_u64 v[216:217], v[212:213], 0, v[216:217]
	v_readlane_b32 s0, v251, 33
	v_readlane_b32 s1, v251, 34
	s_nop 1
	v_or_b32_e32 v218, s0, v156
	v_mov_b32_e32 v221, s1
	v_readlane_b32 s0, v251, 8
	v_readlane_b32 s1, v251, 9
	s_nop 1
	v_lshl_add_u64 v[222:223], s[0:1], 0, v[136:137]
	v_readlane_b32 s0, v251, 31
	s_nop 1
	v_or_b32_e32 v220, s0, v218
	v_lshlrev_b64 v[224:225], 8, v[220:221]
	v_lshl_add_u64 v[224:225], v[222:223], 0, v[224:225]
	v_readlane_b32 s0, v251, 29
	s_nop 1
	v_or_b32_e32 v220, s0, v218
	v_lshlrev_b64 v[226:227], 8, v[220:221]
	v_lshl_add_u64 v[226:227], v[222:223], 0, v[226:227]
	v_readlane_b32 s0, v251, 30
	s_nop 1
	v_or_b32_e32 v220, s0, v218
	v_lshlrev_b64 v[228:229], 8, v[220:221]
	v_lshl_add_u64 v[228:229], v[222:223], 0, v[228:229]
	v_readlane_b32 s0, v251, 32
	s_nop 1
	v_or_b32_e32 v220, s0, v218
	v_lshlrev_b64 v[230:231], 8, v[220:221]
	v_lshl_add_u64 v[230:231], v[222:223], 0, v[230:231]
	global_load_dwordx4 v[32:35], v[214:215], off
	global_load_dwordx4 v[36:39], v[216:217], off
	global_load_dwordx4 v[40:43], v[224:225], off
	global_load_dwordx4 v[44:47], v[226:227], off
	global_load_dwordx4 v[48:51], v[228:229], off
	global_load_dwordx4 v[52:55], v[230:231], off
	global_load_dwordx4 v[56:59], v[214:215], off offset:64
	global_load_dwordx4 v[60:63], v[216:217], off offset:64
	global_load_dwordx4 v[64:67], v[224:225], off offset:64
	global_load_dwordx4 v[68:71], v[226:227], off offset:64
	global_load_dwordx4 v[72:75], v[228:229], off offset:64
	global_load_dwordx4 v[76:79], v[230:231], off offset:64
	global_load_dwordx4 v[80:83], v[214:215], off offset:128
	global_load_dwordx4 v[84:87], v[216:217], off offset:128
	global_load_dwordx4 v[88:91], v[224:225], off offset:128
	global_load_dwordx4 v[92:95], v[226:227], off offset:128
	global_load_dwordx4 v[96:99], v[228:229], off offset:128
	global_load_dwordx4 v[100:103], v[230:231], off offset:128
	global_load_dwordx4 v[104:107], v[214:215], off offset:192
	global_load_dwordx4 v[108:111], v[216:217], off offset:192
	global_load_dwordx4 v[112:115], v[224:225], off offset:192
	global_load_dwordx4 v[116:119], v[226:227], off offset:192
	global_load_dwordx4 v[120:123], v[228:229], off offset:192
	global_load_dwordx4 v[124:127], v[230:231], off offset:192
	v_lshlrev_b32_e32 v136, 1, v156
	v_readlane_b32 s4, v251, 38
	v_readlane_b32 s8, v251, 40
	v_readlane_b32 s0, v251, 35
	v_readlane_b32 s1, v251, 36
	s_waitcnt vmcnt(18)
	v_mfma_f32_16x16x32_bf16 v[202:205], v[32:35], v[40:43], v[16:19]
	v_mfma_f32_16x16x32_bf16 v[16:19], v[32:35], v[52:55], v[12:15]
	v_mfma_f32_16x16x32_bf16 v[12:15], v[36:39], v[40:43], v[28:31]
	v_mfma_f32_16x16x32_bf16 v[206:209], v[32:35], v[44:47], v[4:7]
	v_mfma_f32_16x16x32_bf16 v[4:7], v[36:39], v[48:51], v[8:11]
	v_mfma_f32_16x16x32_bf16 v[8:11], v[36:39], v[44:47], v[20:23]
	v_mfma_f32_16x16x32_bf16 v[20:23], v[32:35], v[48:51], v[0:3]
	v_mfma_f32_16x16x32_bf16 v[0:3], v[36:39], v[52:55], v[24:27]
	s_waitcnt vmcnt(12)
	v_mfma_f32_16x16x32_bf16 v[28:31], v[56:59], v[64:67], v[202:205]
	v_mfma_f32_16x16x32_bf16 v[16:19], v[56:59], v[76:79], v[16:19]
	v_mfma_f32_16x16x32_bf16 v[12:15], v[60:63], v[64:67], v[12:15]
	v_mfma_f32_16x16x32_bf16 v[24:27], v[56:59], v[68:71], v[206:209]
	v_mfma_f32_16x16x32_bf16 v[4:7], v[60:63], v[72:75], v[4:7]
	v_mfma_f32_16x16x32_bf16 v[8:11], v[60:63], v[68:71], v[8:11]
	v_mfma_f32_16x16x32_bf16 v[20:23], v[56:59], v[72:75], v[20:23]
	v_mfma_f32_16x16x32_bf16 v[0:3], v[60:63], v[76:79], v[0:3]
	s_waitcnt vmcnt(6)
	v_mfma_f32_16x16x32_bf16 v[28:31], v[80:83], v[88:91], v[28:31]
	v_mfma_f32_16x16x32_bf16 v[16:19], v[80:83], v[100:103], v[16:19]
	v_mfma_f32_16x16x32_bf16 v[12:15], v[84:87], v[88:91], v[12:15]
	v_mfma_f32_16x16x32_bf16 v[24:27], v[80:83], v[92:95], v[24:27]
	v_mfma_f32_16x16x32_bf16 v[4:7], v[84:87], v[96:99], v[4:7]
	v_mfma_f32_16x16x32_bf16 v[8:11], v[84:87], v[92:95], v[8:11]
	v_mfma_f32_16x16x32_bf16 v[20:23], v[80:83], v[96:99], v[20:23]
	v_mfma_f32_16x16x32_bf16 v[0:3], v[84:87], v[100:103], v[0:3]
	s_waitcnt vmcnt(0)
; __device__ __forceinline__ unsigned f2bf(float f) { return pk2(f, 0.f) & 0xffffu; }
; __device__ __forceinline__ f32x4 mfma16(bf16x8 a, bf16x8 b, f32x4 c) { return __builtin_amdgcn_mfma_f32_16x16x32_bf16(a, b, c, 0, 0, 0); }
; __device__ __forceinline__ float gelu_tanh_f(float x) {
;     const float u = 0.7978845608028654f * (x + 0.044715f * x * x * x);
;     const float t = 1.f - 2.f * __builtin_amdgcn_rcpf(1.f + __expf(2.f * u));
;     return 0.5f * x * (1.f + t);
; }
; __device__ __forceinline__ void ssm_out_unit(const Args& a, int unit) {
;     ...
;     for (int kb = 0; kb < 4; ++kb) {
;         bf16x8 af[2];
; #pragma unroll
;         for (int rk = 0; rk < 2; ++rk) af[rk] = *(const bf16x8*)(HC + ((size_t)(wave * 32 + rk * 16 + r16) * 32 + g) * 128 + kb * 32 + quad * 8);
; #pragma unroll
;         for (int nb = 0; nb < 4; ++nb) { const bf16x8 bf = *(const bf16x8*)(MCT + ((size_t)g * 1024 + (cb * 4 + nb) * 16 + r16) * 128 + kb * 32 + quad * 8);
;             acc[0][nb] = mfma16(af[0], bf, acc[0][nb]); acc[1][nb] = mfma16(af[1], bf, acc[1][nb]); }
;     }
; #pragma unroll
;     for (int rk = 0; rk < 2; ++rk)
; #pragma unroll
;         for (int nb = 0; nb < 4; ++nb)
; #pragma unroll
;             for (int i = 0; i < 4; ++i) { const int chunk = wave * 32 + rk * 16 + quad * 4 + i, t = chunk * 64 + cb * 4 + nb;
;                 YS[(size_t)t * 512 + g * 16 + r16] = (bf16_t)f2bf(gelu_tanh_f(acc[rk][nb][i])); }
	v_mfma_f32_16x16x32_bf16 v[28:31], v[104:107], v[112:115], v[28:31]
	v_mfma_f32_16x16x32_bf16 v[16:19], v[104:107], v[124:127], v[16:19]
	v_mfma_f32_16x16x32_bf16 v[12:15], v[108:111], v[112:115], v[12:15]
	v_mfma_f32_16x16x32_bf16 v[24:27], v[104:107], v[116:119], v[24:27]
	v_mfma_f32_16x16x32_bf16 v[4:7], v[108:111], v[120:123], v[4:7]
	v_mfma_f32_16x16x32_bf16 v[8:11], v[108:111], v[116:119], v[8:11]
	v_mfma_f32_16x16x32_bf16 v[20:23], v[104:107], v[120:123], v[20:23]
	v_mfma_f32_16x16x32_bf16 v[0:3], v[108:111], v[124:127], v[0:3]
	s_nop 7
	v_mul_f32_e32 v35, 0x3d372713, v28
	v_mul_f32_e32 v35, v28, v35
	v_fma_f32 v35, v28, v35, v28
	v_mul_f32_e32 v35, 0x3f4c422a, v35
	v_add_f32_e32 v35, v35, v35
	v_mul_f32_e32 v35, 0x3fb8aa3b, v35
	v_exp_f32_e32 v35, v35
	v_mul_f32_e32 v28, 0.5, v28
	v_lshl_add_u64 v[32:33], s[0:1], 0, v[136:137]
	v_lshl_or_b32 v34, v154, 8, v155
	v_add_f32_e32 v35, 1.0, v35
	v_rcp_f32_e32 v35, v35
	v_readlane_b32 s0, v251, 39
	v_readlane_b32 s1, v251, 37
	v_fma_f32 v35, v35, -2.0, 1.0
	v_add_f32_e32 v35, 1.0, v35
	v_mul_f32_e32 v28, v28, v35
	v_mul_f32_e32 v35, 0x3d372713, v29
	v_mul_f32_e32 v35, v29, v35
	v_fma_f32 v35, v29, v35, v29
	v_mul_f32_e32 v35, 0x3f4c422a, v35
	v_add_f32_e32 v35, v35, v35
	v_mul_f32_e32 v35, 0x3fb8aa3b, v35
	v_exp_f32_e32 v35, v35
	v_mul_f32_e32 v29, 0.5, v29
	v_or_b32_e32 v36, s0, v34
	v_ashrrev_i32_e32 v37, 31, v36
	v_add_f32_e32 v35, 1.0, v35
	v_rcp_f32_e32 v35, v35
	v_lshlrev_b64 v[36:37], 10, v[36:37]
	v_cvt_pk_bf16_f32 v28, v28, s0
	v_lshl_add_u64 v[36:37], v[32:33], 0, v[36:37]
	v_fma_f32 v35, v35, -2.0, 1.0
	v_add_f32_e32 v35, 1.0, v35
	v_mul_f32_e32 v29, v29, v35
	v_mul_f32_e32 v35, 0x3d372713, v30
	v_mul_f32_e32 v35, v30, v35
	v_fma_f32 v35, v30, v35, v30
	v_mul_f32_e32 v35, 0x3f4c422a, v35
	v_add_f32_e32 v35, v35, v35
	v_mul_f32_e32 v35, 0x3fb8aa3b, v35
	v_exp_f32_e32 v35, v35
	v_mul_f32_e32 v30, 0.5, v30
	global_store_short v[36:37], v28, off
	v_or_b32_e32 v28, 64, v34
	v_add_f32_e32 v35, 1.0, v35
	v_rcp_f32_e32 v35, v35
	v_or_b32_e32 v36, s0, v28
	v_ashrrev_i32_e32 v37, 31, v36
	v_lshlrev_b64 v[36:37], 10, v[36:37]
	v_fma_f32 v35, v35, -2.0, 1.0
	v_add_f32_e32 v35, 1.0, v35
	v_mul_f32_e32 v30, v30, v35
	v_mul_f32_e32 v35, 0x3d372713, v31
	v_mul_f32_e32 v35, v31, v35
	v_fma_f32 v35, v31, v35, v31
	v_mul_f32_e32 v35, 0x3f4c422a, v35
	v_add_f32_e32 v35, v35, v35
	v_mul_f32_e32 v35, 0x3fb8aa3b, v35
	v_exp_f32_e32 v35, v35
	v_cvt_pk_bf16_f32 v29, v29, s0
	v_lshl_add_u64 v[36:37], v[32:33], 0, v[36:37]
	global_store_short v[36:37], v29, off
	v_or_b32_e32 v29, 0x80, v34
	v_or_b32_e32 v36, s0, v29
	v_add_f32_e32 v35, 1.0, v35
	v_ashrrev_i32_e32 v37, 31, v36
	v_rcp_f32_e32 v35, v35
	v_lshlrev_b64 v[36:37], 10, v[36:37]
	v_cvt_pk_bf16_f32 v30, v30, s0
	v_lshl_add_u64 v[36:37], v[32:33], 0, v[36:37]
	global_store_short v[36:37], v30, off
	v_or_b32_e32 v30, 0xc0, v34
	v_or_b32_e32 v36, s0, v30
	v_fma_f32 v35, v35, -2.0, 1.0
	v_mul_f32_e32 v31, 0.5, v31
	v_add_f32_e32 v35, 1.0, v35
	v_ashrrev_i32_e32 v37, 31, v36
	v_mul_f32_e32 v31, v31, v35
	v_lshlrev_b64 v[36:37], 10, v[36:37]
	v_cvt_pk_bf16_f32 v31, v31, s0
	v_lshl_add_u64 v[36:37], v[32:33], 0, v[36:37]
	global_store_short v[36:37], v31, off
	v_mul_f32_e32 v31, 0x3d372713, v24
	v_mul_f32_e32 v31, v24, v31
	v_fma_f32 v31, v24, v31, v24
	v_mul_f32_e32 v31, 0x3f4c422a, v31
	v_add_f32_e32 v31, v31, v31
	v_mul_f32_e32 v31, 0x3fb8aa3b, v31
	v_exp_f32_e32 v31, v31
	v_mul_f32_e32 v24, 0.5, v24
	v_or_b32_e32 v36, s1, v34
	v_ashrrev_i32_e32 v37, 31, v36
	v_add_f32_e32 v31, 1.0, v31
	v_rcp_f32_e32 v31, v31
	v_lshlrev_b64 v[36:37], 10, v[36:37]
	v_lshl_add_u64 v[36:37], v[32:33], 0, v[36:37]
	v_fma_f32 v31, v31, -2.0, 1.0
	v_add_f32_e32 v31, 1.0, v31
	v_mul_f32_e32 v24, v24, v31
	v_mul_f32_e32 v31, 0x3d372713, v25
	v_mul_f32_e32 v31, v25, v31
	v_fma_f32 v31, v25, v31, v25
	v_mul_f32_e32 v31, 0x3f4c422a, v31
	v_add_f32_e32 v31, v31, v31
	v_mul_f32_e32 v31, 0x3fb8aa3b, v31
	v_exp_f32_e32 v31, v31
	v_cvt_pk_bf16_f32 v24, v24, s0
	v_mul_f32_e32 v25, 0.5, v25
	global_store_short v[36:37], v24, off
	v_add_f32_e32 v31, 1.0, v31
	v_rcp_f32_e32 v31, v31
	v_or_b32_e32 v24, s1, v28
	v_fma_f32 v31, v31, -2.0, 1.0
	v_add_f32_e32 v31, 1.0, v31
	v_mul_f32_e32 v25, v25, v31
	v_cvt_pk_bf16_f32 v31, v25, s0
	v_ashrrev_i32_e32 v25, 31, v24
	v_lshlrev_b64 v[24:25], 10, v[24:25]
	v_lshl_add_u64 v[24:25], v[32:33], 0, v[24:25]
	global_store_short v[24:25], v31, off
	v_mul_f32_e32 v25, 0x3d372713, v26
	v_mul_f32_e32 v25, v26, v25
	v_fma_f32 v25, v26, v25, v26
	v_mul_f32_e32 v25, 0x3f4c422a, v25
	v_add_f32_e32 v25, v25, v25
	v_mul_f32_e32 v25, 0x3fb8aa3b, v25
	v_exp_f32_e32 v25, v25
	v_mul_f32_e32 v26, 0.5, v26
	v_or_b32_e32 v24, s1, v29
	v_add_f32_e32 v25, 1.0, v25
	v_rcp_f32_e32 v25, v25
	s_nop 0
	v_fma_f32 v25, v25, -2.0, 1.0
	v_add_f32_e32 v25, 1.0, v25
	v_mul_f32_e32 v25, v26, v25
	v_cvt_pk_bf16_f32 v26, v25, s0
	v_ashrrev_i32_e32 v25, 31, v24
	v_lshlrev_b64 v[24:25], 10, v[24:25]
	v_lshl_add_u64 v[24:25], v[32:33], 0, v[24:25]
	global_store_short v[24:25], v26, off
	v_mul_f32_e32 v25, 0x3d372713, v27
	v_mul_f32_e32 v25, v27, v25
	v_fma_f32 v25, v27, v25, v27
	v_mul_f32_e32 v25, 0x3f4c422a, v25
	v_add_f32_e32 v25, v25, v25
	v_mul_f32_e32 v25, 0x3fb8aa3b, v25
	v_exp_f32_e32 v25, v25
	v_mul_f32_e32 v26, 0.5, v27
	v_or_b32_e32 v24, s1, v30
	v_add_f32_e32 v25, 1.0, v25
	v_rcp_f32_e32 v25, v25
	s_nop 0
	v_fma_f32 v25, v25, -2.0, 1.0
	v_add_f32_e32 v25, 1.0, v25
	v_mul_f32_e32 v25, v26, v25
	v_cvt_pk_bf16_f32 v26, v25, s0
	v_ashrrev_i32_e32 v25, 31, v24
	v_lshlrev_b64 v[24:25], 10, v[24:25]
	v_lshl_add_u64 v[24:25], v[32:33], 0, v[24:25]
	global_store_short v[24:25], v26, off
; __device__ __forceinline__ unsigned f2bf(float f) { return pk2(f, 0.f) & 0xffffu; }
; __device__ __forceinline__ float gelu_tanh_f(float x) {
;     const float u = 0.7978845608028654f * (x + 0.044715f * x * x * x);
;     const float t = 1.f - 2.f * __builtin_amdgcn_rcpf(1.f + __expf(2.f * u));
;     return 0.5f * x * (1.f + t);
; }
; __device__ __forceinline__ void ssm_out_unit(const Args& a, int unit) {
;     ...
; #pragma unroll
;     for (int rk = 0; rk < 2; ++rk)
; #pragma unroll
;         for (int nb = 0; nb < 4; ++nb)
; #pragma unroll
;             for (int i = 0; i < 4; ++i) { const int chunk = wave * 32 + rk * 16 + quad * 4 + i, t = chunk * 64 + cb * 4 + nb;
;                 YS[(size_t)t * 512 + g * 16 + r16] = (bf16_t)f2bf(gelu_tanh_f(acc[rk][nb][i])); }
	v_mul_f32_e32 v25, 0x3d372713, v20
	v_mul_f32_e32 v25, v20, v25
	v_fma_f32 v25, v20, v25, v20
	v_mul_f32_e32 v25, 0x3f4c422a, v25
	v_add_f32_e32 v25, v25, v25
	v_mul_f32_e32 v25, 0x3fb8aa3b, v25
	v_exp_f32_e32 v25, v25
	v_or_b32_e32 v24, s4, v34
	v_mul_f32_e32 v20, 0.5, v20
	v_add_f32_e32 v25, 1.0, v25
	v_rcp_f32_e32 v25, v25
	s_nop 0
	v_fma_f32 v25, v25, -2.0, 1.0
	v_add_f32_e32 v25, 1.0, v25
	v_mul_f32_e32 v20, v20, v25
	v_ashrrev_i32_e32 v25, 31, v24
	v_lshlrev_b64 v[24:25], 10, v[24:25]
	v_cvt_pk_bf16_f32 v20, v20, s0
	v_lshl_add_u64 v[24:25], v[32:33], 0, v[24:25]
	global_store_short v[24:25], v20, off
	v_mul_f32_e32 v24, 0x3d372713, v21
	v_mul_f32_e32 v24, v21, v24
	v_fma_f32 v24, v21, v24, v21
	v_mul_f32_e32 v24, 0x3f4c422a, v24
	v_add_f32_e32 v24, v24, v24
	v_mul_f32_e32 v24, 0x3fb8aa3b, v24
	v_exp_f32_e32 v24, v24
	v_mul_f32_e32 v21, 0.5, v21
	v_or_b32_e32 v20, s4, v28
	v_add_f32_e32 v24, 1.0, v24
	v_rcp_f32_e32 v24, v24
	s_nop 0
	v_fma_f32 v24, v24, -2.0, 1.0
	v_add_f32_e32 v24, 1.0, v24
	v_mul_f32_e32 v21, v21, v24
	v_cvt_pk_bf16_f32 v24, v21, s0
	v_ashrrev_i32_e32 v21, 31, v20
	v_lshlrev_b64 v[20:21], 10, v[20:21]
	v_lshl_add_u64 v[20:21], v[32:33], 0, v[20:21]
	global_store_short v[20:21], v24, off
	v_mul_f32_e32 v21, 0x3d372713, v22
	v_mul_f32_e32 v21, v22, v21
	v_fma_f32 v21, v22, v21, v22
	v_mul_f32_e32 v21, 0x3f4c422a, v21
	v_add_f32_e32 v21, v21, v21
	v_mul_f32_e32 v21, 0x3fb8aa3b, v21
	v_exp_f32_e32 v21, v21
	v_mul_f32_e32 v22, 0.5, v22
	v_or_b32_e32 v20, s4, v29
	v_add_f32_e32 v21, 1.0, v21
	v_rcp_f32_e32 v21, v21
	s_nop 0
	v_fma_f32 v21, v21, -2.0, 1.0
	v_add_f32_e32 v21, 1.0, v21
	v_mul_f32_e32 v21, v22, v21
	v_cvt_pk_bf16_f32 v22, v21, s0
	v_ashrrev_i32_e32 v21, 31, v20
	v_lshlrev_b64 v[20:21], 10, v[20:21]
	v_lshl_add_u64 v[20:21], v[32:33], 0, v[20:21]
	global_store_short v[20:21], v22, off
	v_mul_f32_e32 v21, 0x3d372713, v23
	v_mul_f32_e32 v21, v23, v21
	v_fma_f32 v21, v23, v21, v23
	v_mul_f32_e32 v21, 0x3f4c422a, v21
	v_add_f32_e32 v21, v21, v21
	v_mul_f32_e32 v21, 0x3fb8aa3b, v21
	v_exp_f32_e32 v21, v21
	v_mul_f32_e32 v22, 0.5, v23
	v_or_b32_e32 v20, s4, v30
	v_add_f32_e32 v21, 1.0, v21
	v_rcp_f32_e32 v21, v21
	s_nop 0
	v_fma_f32 v21, v21, -2.0, 1.0
	v_add_f32_e32 v21, 1.0, v21
	v_mul_f32_e32 v21, v22, v21
	v_cvt_pk_bf16_f32 v22, v21, s0
	v_ashrrev_i32_e32 v21, 31, v20
	v_lshlrev_b64 v[20:21], 10, v[20:21]
	v_lshl_add_u64 v[20:21], v[32:33], 0, v[20:21]
	global_store_short v[20:21], v22, off
	v_mul_f32_e32 v21, 0x3d372713, v16
	v_mul_f32_e32 v21, v16, v21
	v_fma_f32 v21, v16, v21, v16
	v_mul_f32_e32 v21, 0x3f4c422a, v21
	v_add_f32_e32 v21, v21, v21
	v_mul_f32_e32 v21, 0x3fb8aa3b, v21
	v_exp_f32_e32 v21, v21
	v_or_b32_e32 v20, s8, v34
	v_mul_f32_e32 v16, 0.5, v16
	v_add_f32_e32 v21, 1.0, v21
	v_rcp_f32_e32 v21, v21
	s_nop 0
	v_fma_f32 v21, v21, -2.0, 1.0
	v_add_f32_e32 v21, 1.0, v21
	v_mul_f32_e32 v16, v16, v21
	v_ashrrev_i32_e32 v21, 31, v20
	v_lshlrev_b64 v[20:21], 10, v[20:21]
	v_cvt_pk_bf16_f32 v16, v16, s0
	v_lshl_add_u64 v[20:21], v[32:33], 0, v[20:21]
	global_store_short v[20:21], v16, off
	v_mul_f32_e32 v20, 0x3d372713, v17
	v_mul_f32_e32 v20, v17, v20
	v_fma_f32 v20, v17, v20, v17
	v_mul_f32_e32 v20, 0x3f4c422a, v20
	v_add_f32_e32 v20, v20, v20
	v_mul_f32_e32 v20, 0x3fb8aa3b, v20
	v_exp_f32_e32 v20, v20
	v_mul_f32_e32 v17, 0.5, v17
	v_or_b32_e32 v16, s8, v28
	v_add_f32_e32 v20, 1.0, v20
	v_rcp_f32_e32 v20, v20
	s_nop 0
	v_fma_f32 v20, v20, -2.0, 1.0
	v_add_f32_e32 v20, 1.0, v20
	v_mul_f32_e32 v17, v17, v20
	v_cvt_pk_bf16_f32 v20, v17, s0
	v_ashrrev_i32_e32 v17, 31, v16
	v_lshlrev_b64 v[16:17], 10, v[16:17]
	v_lshl_add_u64 v[16:17], v[32:33], 0, v[16:17]
	global_store_short v[16:17], v20, off
	v_mul_f32_e32 v17, 0x3d372713, v18
	v_mul_f32_e32 v17, v18, v17
	v_fma_f32 v17, v18, v17, v18
	v_mul_f32_e32 v17, 0x3f4c422a, v17
	v_add_f32_e32 v17, v17, v17
	v_mul_f32_e32 v17, 0x3fb8aa3b, v17
	v_exp_f32_e32 v17, v17
	v_mul_f32_e32 v18, 0.5, v18
	v_or_b32_e32 v16, s8, v29
	v_add_f32_e32 v17, 1.0, v17
	v_rcp_f32_e32 v17, v17
	s_nop 0
	v_fma_f32 v17, v17, -2.0, 1.0
	v_add_f32_e32 v17, 1.0, v17
	v_mul_f32_e32 v17, v18, v17
	v_cvt_pk_bf16_f32 v18, v17, s0
	v_ashrrev_i32_e32 v17, 31, v16
	v_lshlrev_b64 v[16:17], 10, v[16:17]
	v_lshl_add_u64 v[16:17], v[32:33], 0, v[16:17]
	global_store_short v[16:17], v18, off
	v_mul_f32_e32 v17, 0x3d372713, v19
	v_mul_f32_e32 v17, v19, v17
	v_fma_f32 v17, v19, v17, v19
	v_mul_f32_e32 v17, 0x3f4c422a, v17
	v_add_f32_e32 v17, v17, v17
	v_mul_f32_e32 v17, 0x3fb8aa3b, v17
	v_exp_f32_e32 v17, v17
	v_mul_f32_e32 v18, 0.5, v19
	v_or_b32_e32 v16, s8, v30
	v_add_f32_e32 v17, 1.0, v17
	v_rcp_f32_e32 v17, v17
	s_nop 0
	v_fma_f32 v17, v17, -2.0, 1.0
	v_add_f32_e32 v17, 1.0, v17
	v_mul_f32_e32 v17, v18, v17
	v_cvt_pk_bf16_f32 v18, v17, s0
	v_ashrrev_i32_e32 v17, 31, v16
	v_lshlrev_b64 v[16:17], 10, v[16:17]
	v_lshl_add_u64 v[16:17], v[32:33], 0, v[16:17]
	global_store_short v[16:17], v18, off
	v_mul_f32_e32 v17, 0x3d372713, v12
	v_mul_f32_e32 v17, v12, v17
	v_fma_f32 v17, v12, v17, v12
	v_mul_f32_e32 v17, 0x3f4c422a, v17
	v_add_f32_e32 v17, v17, v17
	v_mul_f32_e32 v17, 0x3fb8aa3b, v17
	v_exp_f32_e32 v17, v17
	v_mul_f32_e32 v12, 0.5, v12
	v_or_b32_e32 v16, 0x400, v34
	v_or_b32_e32 v18, s0, v16
	v_add_f32_e32 v17, 1.0, v17
	v_rcp_f32_e32 v17, v17
	v_ashrrev_i32_e32 v19, 31, v18
	v_lshlrev_b64 v[18:19], 10, v[18:19]
	v_lshl_add_u64 v[18:19], v[32:33], 0, v[18:19]
	v_fma_f32 v17, v17, -2.0, 1.0
	v_add_f32_e32 v17, 1.0, v17
	v_mul_f32_e32 v12, v12, v17
	v_mul_f32_e32 v17, 0x3d372713, v13
	v_mul_f32_e32 v17, v13, v17
	v_fma_f32 v17, v13, v17, v13
	v_mul_f32_e32 v17, 0x3f4c422a, v17
	v_add_f32_e32 v17, v17, v17
; __device__ __forceinline__ unsigned f2bf(float f) { return pk2(f, 0.f) & 0xffffu; }
; __device__ __forceinline__ float gelu_tanh_f(float x) {
;     const float u = 0.7978845608028654f * (x + 0.044715f * x * x * x);
;     const float t = 1.f - 2.f * __builtin_amdgcn_rcpf(1.f + __expf(2.f * u));
;     return 0.5f * x * (1.f + t);
; }
; __device__ __forceinline__ void ssm_out_unit(const Args& a, int unit) {
;     ...
; #pragma unroll
;     for (int rk = 0; rk < 2; ++rk)
; #pragma unroll
;         for (int nb = 0; nb < 4; ++nb)
; #pragma unroll
;             for (int i = 0; i < 4; ++i) { const int chunk = wave * 32 + rk * 16 + quad * 4 + i, t = chunk * 64 + cb * 4 + nb;
;                 YS[(size_t)t * 512 + g * 16 + r16] = (bf16_t)f2bf(gelu_tanh_f(acc[rk][nb][i])); }
	v_mul_f32_e32 v17, 0x3fb8aa3b, v17
	v_exp_f32_e32 v17, v17
	v_mul_f32_e32 v13, 0.5, v13
	v_cvt_pk_bf16_f32 v12, v12, s0
	global_store_short v[18:19], v12, off
	v_add_f32_e32 v17, 1.0, v17
	v_rcp_f32_e32 v17, v17
	v_or_b32_e32 v12, 0x440, v34
	v_or_b32_e32 v18, s0, v12
	v_ashrrev_i32_e32 v19, 31, v18
	v_fma_f32 v17, v17, -2.0, 1.0
	v_add_f32_e32 v17, 1.0, v17
	v_mul_f32_e32 v13, v13, v17
	v_mul_f32_e32 v17, 0x3d372713, v14
	v_mul_f32_e32 v17, v14, v17
	v_fma_f32 v17, v14, v17, v14
	v_mul_f32_e32 v17, 0x3f4c422a, v17
	v_add_f32_e32 v17, v17, v17
	v_mul_f32_e32 v17, 0x3fb8aa3b, v17
	v_exp_f32_e32 v17, v17
	v_mul_f32_e32 v14, 0.5, v14
	v_lshlrev_b64 v[18:19], 10, v[18:19]
	v_cvt_pk_bf16_f32 v13, v13, s0
	v_add_f32_e32 v17, 1.0, v17
	v_rcp_f32_e32 v17, v17
	v_lshl_add_u64 v[18:19], v[32:33], 0, v[18:19]
	global_store_short v[18:19], v13, off
	v_or_b32_e32 v13, 0x480, v34
	v_fma_f32 v17, v17, -2.0, 1.0
	v_add_f32_e32 v17, 1.0, v17
	v_mul_f32_e32 v14, v14, v17
	v_mul_f32_e32 v17, 0x3d372713, v15
	v_mul_f32_e32 v17, v15, v17
	v_fma_f32 v17, v15, v17, v15
	v_mul_f32_e32 v17, 0x3f4c422a, v17
	v_add_f32_e32 v17, v17, v17
	v_mul_f32_e32 v17, 0x3fb8aa3b, v17
	v_exp_f32_e32 v17, v17
	v_or_b32_e32 v18, s0, v13
	v_ashrrev_i32_e32 v19, 31, v18
	v_lshlrev_b64 v[18:19], 10, v[18:19]
	v_add_f32_e32 v17, 1.0, v17
	v_rcp_f32_e32 v17, v17
	v_cvt_pk_bf16_f32 v14, v14, s0
	v_lshl_add_u64 v[18:19], v[32:33], 0, v[18:19]
	global_store_short v[18:19], v14, off
	v_or_b32_e32 v14, 0x4c0, v34
	v_or_b32_e32 v18, s0, v14
	v_fma_f32 v17, v17, -2.0, 1.0
	v_mul_f32_e32 v15, 0.5, v15
	v_add_f32_e32 v17, 1.0, v17
	v_ashrrev_i32_e32 v19, 31, v18
	v_mul_f32_e32 v15, v15, v17
	v_lshlrev_b64 v[18:19], 10, v[18:19]
	v_cvt_pk_bf16_f32 v15, v15, s0
	v_lshl_add_u64 v[18:19], v[32:33], 0, v[18:19]
	global_store_short v[18:19], v15, off
	v_mul_f32_e32 v15, 0x3d372713, v8
	v_mul_f32_e32 v15, v8, v15
	v_fma_f32 v15, v8, v15, v8
	v_mul_f32_e32 v15, 0x3f4c422a, v15
	v_add_f32_e32 v15, v15, v15
	v_mul_f32_e32 v15, 0x3fb8aa3b, v15
	v_exp_f32_e32 v15, v15
	v_mul_f32_e32 v8, 0.5, v8
	v_or_b32_e32 v18, s1, v16
	v_ashrrev_i32_e32 v19, 31, v18
	v_add_f32_e32 v15, 1.0, v15
	v_rcp_f32_e32 v15, v15
	v_lshlrev_b64 v[18:19], 10, v[18:19]
	v_lshl_add_u64 v[18:19], v[32:33], 0, v[18:19]
	v_fma_f32 v15, v15, -2.0, 1.0
	v_add_f32_e32 v15, 1.0, v15
	v_mul_f32_e32 v8, v8, v15
	v_mul_f32_e32 v15, 0x3d372713, v9
	v_mul_f32_e32 v15, v9, v15
	v_fma_f32 v15, v9, v15, v9
	v_mul_f32_e32 v15, 0x3f4c422a, v15
	v_add_f32_e32 v15, v15, v15
	v_mul_f32_e32 v15, 0x3fb8aa3b, v15
	v_exp_f32_e32 v15, v15
	v_cvt_pk_bf16_f32 v8, v8, s0
	v_mul_f32_e32 v9, 0.5, v9
	global_store_short v[18:19], v8, off
	v_add_f32_e32 v15, 1.0, v15
	v_rcp_f32_e32 v15, v15
	v_or_b32_e32 v8, s1, v12
	v_fma_f32 v15, v15, -2.0, 1.0
	v_add_f32_e32 v15, 1.0, v15
	v_mul_f32_e32 v9, v9, v15
	v_cvt_pk_bf16_f32 v15, v9, s0
	v_ashrrev_i32_e32 v9, 31, v8
	v_lshlrev_b64 v[8:9], 10, v[8:9]
	v_lshl_add_u64 v[8:9], v[32:33], 0, v[8:9]
	global_store_short v[8:9], v15, off
	v_mul_f32_e32 v9, 0x3d372713, v10
	v_mul_f32_e32 v9, v10, v9
	v_fma_f32 v9, v10, v9, v10
	v_mul_f32_e32 v9, 0x3f4c422a, v9
	v_add_f32_e32 v9, v9, v9
	v_mul_f32_e32 v9, 0x3fb8aa3b, v9
	v_exp_f32_e32 v9, v9
	v_mul_f32_e32 v10, 0.5, v10
	v_or_b32_e32 v8, s1, v13
	v_add_f32_e32 v9, 1.0, v9
	v_rcp_f32_e32 v9, v9
	s_nop 0
	v_fma_f32 v9, v9, -2.0, 1.0
	v_add_f32_e32 v9, 1.0, v9
	v_mul_f32_e32 v9, v10, v9
	v_cvt_pk_bf16_f32 v10, v9, s0
	v_ashrrev_i32_e32 v9, 31, v8
	v_lshlrev_b64 v[8:9], 10, v[8:9]
	v_lshl_add_u64 v[8:9], v[32:33], 0, v[8:9]
	global_store_short v[8:9], v10, off
	v_mul_f32_e32 v9, 0x3d372713, v11
	v_mul_f32_e32 v9, v11, v9
	v_fma_f32 v9, v11, v9, v11
	v_mul_f32_e32 v9, 0x3f4c422a, v9
	v_add_f32_e32 v9, v9, v9
	v_mul_f32_e32 v9, 0x3fb8aa3b, v9
	v_exp_f32_e32 v9, v9
	v_mul_f32_e32 v10, 0.5, v11
	v_or_b32_e32 v8, s1, v14
	v_add_f32_e32 v9, 1.0, v9
	v_rcp_f32_e32 v9, v9
	s_nop 0
	v_fma_f32 v9, v9, -2.0, 1.0
	v_add_f32_e32 v9, 1.0, v9
	v_mul_f32_e32 v9, v10, v9
	v_cvt_pk_bf16_f32 v10, v9, s0
	v_ashrrev_i32_e32 v9, 31, v8
	v_lshlrev_b64 v[8:9], 10, v[8:9]
	v_lshl_add_u64 v[8:9], v[32:33], 0, v[8:9]
	global_store_short v[8:9], v10, off
	v_mul_f32_e32 v9, 0x3d372713, v4
	v_mul_f32_e32 v9, v4, v9
	v_fma_f32 v9, v4, v9, v4
	v_mul_f32_e32 v9, 0x3f4c422a, v9
	v_add_f32_e32 v9, v9, v9
	v_mul_f32_e32 v9, 0x3fb8aa3b, v9
	v_exp_f32_e32 v9, v9
; __device__ __forceinline__ unsigned f2bf(float f) { return pk2(f, 0.f) & 0xffffu; }
; __device__ __forceinline__ float gelu_tanh_f(float x) {
;     const float u = 0.7978845608028654f * (x + 0.044715f * x * x * x);
;     const float t = 1.f - 2.f * __builtin_amdgcn_rcpf(1.f + __expf(2.f * u));
;     return 0.5f * x * (1.f + t);
; }
; __device__ __forceinline__ void ssm_out_unit(const Args& a, int unit) {
;     ...
; #pragma unroll
;     for (int rk = 0; rk < 2; ++rk)
; #pragma unroll
;         for (int nb = 0; nb < 4; ++nb)
; #pragma unroll
;             for (int i = 0; i < 4; ++i) { const int chunk = wave * 32 + rk * 16 + quad * 4 + i, t = chunk * 64 + cb * 4 + nb;
;                 YS[(size_t)t * 512 + g * 16 + r16] = (bf16_t)f2bf(gelu_tanh_f(acc[rk][nb][i])); }
	v_or_b32_e32 v8, s4, v16
	v_mul_f32_e32 v4, 0.5, v4
	v_add_f32_e32 v9, 1.0, v9
	v_rcp_f32_e32 v9, v9
	s_nop 0
	v_fma_f32 v9, v9, -2.0, 1.0
	v_add_f32_e32 v9, 1.0, v9
	v_mul_f32_e32 v4, v4, v9
	v_ashrrev_i32_e32 v9, 31, v8
	v_lshlrev_b64 v[8:9], 10, v[8:9]
	v_cvt_pk_bf16_f32 v4, v4, s0
	v_lshl_add_u64 v[8:9], v[32:33], 0, v[8:9]
	global_store_short v[8:9], v4, off
	v_mul_f32_e32 v8, 0x3d372713, v5
	v_mul_f32_e32 v8, v5, v8
	v_fma_f32 v8, v5, v8, v5
	v_mul_f32_e32 v8, 0x3f4c422a, v8
	v_add_f32_e32 v8, v8, v8
	v_mul_f32_e32 v8, 0x3fb8aa3b, v8
	v_exp_f32_e32 v8, v8
	v_mul_f32_e32 v5, 0.5, v5
	v_or_b32_e32 v4, s4, v12
	v_add_f32_e32 v8, 1.0, v8
	v_rcp_f32_e32 v8, v8
	s_nop 0
	v_fma_f32 v8, v8, -2.0, 1.0
	v_add_f32_e32 v8, 1.0, v8
	v_mul_f32_e32 v5, v5, v8
	v_cvt_pk_bf16_f32 v8, v5, s0
	v_ashrrev_i32_e32 v5, 31, v4
	v_lshlrev_b64 v[4:5], 10, v[4:5]
	v_lshl_add_u64 v[4:5], v[32:33], 0, v[4:5]
	global_store_short v[4:5], v8, off
	v_mul_f32_e32 v5, 0x3d372713, v6
	v_mul_f32_e32 v5, v6, v5
	v_fma_f32 v5, v6, v5, v6
	v_mul_f32_e32 v5, 0x3f4c422a, v5
	v_add_f32_e32 v5, v5, v5
	v_mul_f32_e32 v5, 0x3fb8aa3b, v5
	v_exp_f32_e32 v5, v5
	v_mul_f32_e32 v6, 0.5, v6
	v_or_b32_e32 v4, s4, v13
	v_add_f32_e32 v5, 1.0, v5
	v_rcp_f32_e32 v5, v5
	s_nop 0
	v_fma_f32 v5, v5, -2.0, 1.0
	v_add_f32_e32 v5, 1.0, v5
	v_mul_f32_e32 v5, v6, v5
	v_cvt_pk_bf16_f32 v6, v5, s0
	v_ashrrev_i32_e32 v5, 31, v4
	v_lshlrev_b64 v[4:5], 10, v[4:5]
	v_lshl_add_u64 v[4:5], v[32:33], 0, v[4:5]
	global_store_short v[4:5], v6, off
	v_mul_f32_e32 v5, 0x3d372713, v7
	v_mul_f32_e32 v5, v7, v5
	v_fma_f32 v5, v7, v5, v7
	v_mul_f32_e32 v5, 0x3f4c422a, v5
	v_add_f32_e32 v5, v5, v5
	v_mul_f32_e32 v5, 0x3fb8aa3b, v5
	v_exp_f32_e32 v5, v5
	v_mul_f32_e32 v6, 0.5, v7
	v_or_b32_e32 v4, s4, v14
	v_add_f32_e32 v5, 1.0, v5
	v_rcp_f32_e32 v5, v5
	s_nop 0
	v_fma_f32 v5, v5, -2.0, 1.0
	v_add_f32_e32 v5, 1.0, v5
	v_mul_f32_e32 v5, v6, v5
	v_cvt_pk_bf16_f32 v6, v5, s0
	v_ashrrev_i32_e32 v5, 31, v4
	v_lshlrev_b64 v[4:5], 10, v[4:5]
	v_lshl_add_u64 v[4:5], v[32:33], 0, v[4:5]
	global_store_short v[4:5], v6, off
	v_mul_f32_e32 v5, 0x3d372713, v0
	v_mul_f32_e32 v5, v0, v5
	v_fma_f32 v5, v0, v5, v0
	v_mul_f32_e32 v5, 0x3f4c422a, v5
	v_add_f32_e32 v5, v5, v5
	v_mul_f32_e32 v5, 0x3fb8aa3b, v5
	v_exp_f32_e32 v5, v5
	v_or_b32_e32 v4, s8, v16
	v_mul_f32_e32 v0, 0.5, v0
	v_add_f32_e32 v5, 1.0, v5
	v_rcp_f32_e32 v5, v5
	s_nop 0
	v_fma_f32 v5, v5, -2.0, 1.0
	v_add_f32_e32 v5, 1.0, v5
	v_mul_f32_e32 v0, v0, v5
	v_ashrrev_i32_e32 v5, 31, v4
	v_lshlrev_b64 v[4:5], 10, v[4:5]
	v_cvt_pk_bf16_f32 v0, v0, s0
	v_lshl_add_u64 v[4:5], v[32:33], 0, v[4:5]
	global_store_short v[4:5], v0, off
	v_mul_f32_e32 v4, 0x3d372713, v1
	v_mul_f32_e32 v4, v1, v4
	v_fma_f32 v4, v1, v4, v1
	v_mul_f32_e32 v4, 0x3f4c422a, v4
	v_add_f32_e32 v4, v4, v4
	v_mul_f32_e32 v4, 0x3fb8aa3b, v4
	v_exp_f32_e32 v4, v4
	v_mul_f32_e32 v1, 0.5, v1
	v_or_b32_e32 v0, s8, v12
	v_add_f32_e32 v4, 1.0, v4
	v_rcp_f32_e32 v4, v4
	s_nop 0
	v_fma_f32 v4, v4, -2.0, 1.0
	v_add_f32_e32 v4, 1.0, v4
	v_mul_f32_e32 v1, v1, v4
	v_cvt_pk_bf16_f32 v4, v1, s0
	v_ashrrev_i32_e32 v1, 31, v0
	v_lshlrev_b64 v[0:1], 10, v[0:1]
	v_lshl_add_u64 v[0:1], v[32:33], 0, v[0:1]
	global_store_short v[0:1], v4, off
	v_mul_f32_e32 v1, 0x3d372713, v2
	v_mul_f32_e32 v1, v2, v1
	v_fma_f32 v1, v2, v1, v2
	v_mul_f32_e32 v1, 0x3f4c422a, v1
	v_add_f32_e32 v1, v1, v1
	v_mul_f32_e32 v1, 0x3fb8aa3b, v1
	v_exp_f32_e32 v1, v1
	v_mul_f32_e32 v2, 0.5, v2
	v_or_b32_e32 v0, s8, v13
	v_add_f32_e32 v1, 1.0, v1
	v_rcp_f32_e32 v1, v1
	s_nop 0
	v_fma_f32 v1, v1, -2.0, 1.0
	v_add_f32_e32 v1, 1.0, v1
	v_mul_f32_e32 v1, v2, v1
	v_cvt_pk_bf16_f32 v2, v1, s0
	v_ashrrev_i32_e32 v1, 31, v0
	v_lshlrev_b64 v[0:1], 10, v[0:1]
	v_lshl_add_u64 v[0:1], v[32:33], 0, v[0:1]
	global_store_short v[0:1], v2, off
	v_mul_f32_e32 v1, 0x3d372713, v3
	v_mul_f32_e32 v1, v3, v1
	v_fma_f32 v1, v3, v1, v3
	v_mul_f32_e32 v1, 0x3f4c422a, v1
	v_add_f32_e32 v1, v1, v1
	v_mul_f32_e32 v1, 0x3fb8aa3b, v1
	v_exp_f32_e32 v1, v1
	v_mul_f32_e32 v2, 0.5, v3
	v_or_b32_e32 v0, s8, v14
	v_add_f32_e32 v1, 1.0, v1
	v_rcp_f32_e32 v1, v1
	s_nop 0
	v_fma_f32 v1, v1, -2.0, 1.0
	v_add_f32_e32 v1, 1.0, v1
	v_mul_f32_e32 v1, v2, v1
	v_cvt_pk_bf16_f32 v2, v1, s0
	v_ashrrev_i32_e32 v1, 31, v0
	v_lshlrev_b64 v[0:1], 10, v[0:1]
	v_lshl_add_u64 v[0:1], v[32:33], 0, v[0:1]
	global_store_short v[0:1], v2, off

;     __device__ __forceinline__ void operator()(AccRef acc, const Unit& u, int wr, int wc, int fr, int fq) const {
;         const int row0 = u.pm * BM + wr * 64 + fr, col0 = u.pn * 128 + wc * 32 + 8 * fq;
; #pragma unroll
;         for (int ai = 0; ai < 2; ++ai)
; #pragma unroll
;             for (int m = 0; m < 4; ++m) {
;                 const int row = row0 + ai * HALF + m * 16;
;                 const float rinv = rsqrtf((float)rss[row] * (1.f / (16777216.f * DM)) + EPS);
;                 const float nrl = rinv * -1.4426950408889634f, r2 = rinv * rinv;
;                 unsigned ow[4];
; #pragma unroll
;                 for (int n = 0; n < 2; ++n)
; #pragma unroll
;                     for (int jp = 0; jp < 2; ++jp) {
;                         const f32v2_t ag = {acc[ai][0][m][n][2 * jp], acc[ai][0][m][n][2 * jp + 1]}, au = {acc[ai][1][m][n][2 * jp], acc[ai][1][m][n][2 * jp + 1]};
.LBB0_748:
	v_lshl_add_u32 v156, s27, 8, v162
	v_ashrrev_i32_e32 v157, 31, v156
	v_lshl_add_u64 v[158:159], v[156:157], 3, s[40:41]
	global_load_dwordx2 v[182:183], v[158:159], off
	global_load_dwordx2 v[184:185], v[158:159], off offset:128
	global_load_dwordx2 v[186:187], v[158:159], off offset:256
	global_load_dwordx2 v[188:189], v[158:159], off offset:384
	global_load_dwordx2 v[194:195], v[158:159], off offset:1024
	global_load_dwordx2 v[196:197], v[158:159], off offset:1152
	global_load_dwordx2 v[198:199], v[158:159], off offset:1280
	global_load_dwordx2 v[200:201], v[158:159], off offset:1408
	v_pk_mul_f32 v[120:121], v[124:125], v[120:121]
	v_pk_mul_f32 v[122:123], v[126:127], v[122:123]
	v_pk_mul_f32 v[112:113], v[116:117], v[112:113]
	v_pk_mul_f32 v[114:115], v[118:119], v[114:115]
	v_pk_mul_f32 v[104:105], v[108:109], v[104:105]
	v_pk_mul_f32 v[106:107], v[110:111], v[106:107]
	v_pk_mul_f32 v[96:97], v[100:101], v[96:97]
	v_pk_mul_f32 v[98:99], v[102:103], v[98:99]
	v_pk_mul_f32 v[88:89], v[92:93], v[88:89]
	v_pk_mul_f32 v[90:91], v[94:95], v[90:91]
	v_pk_mul_f32 v[80:81], v[84:85], v[80:81]
	v_pk_mul_f32 v[82:83], v[86:87], v[82:83]
	v_pk_mul_f32 v[72:73], v[76:77], v[72:73]
	v_pk_mul_f32 v[74:75], v[78:79], v[74:75]
	v_pk_mul_f32 v[64:65], v[68:69], v[64:65]
	v_pk_mul_f32 v[66:67], v[70:71], v[66:67]
	v_pk_mul_f32 v[56:57], v[60:61], v[56:57]
	v_pk_mul_f32 v[58:59], v[62:63], v[58:59]
	v_pk_mul_f32 v[48:49], v[52:53], v[48:49]
	v_pk_mul_f32 v[50:51], v[54:55], v[50:51]
	v_pk_mul_f32 v[40:41], v[44:45], v[40:41]
	v_pk_mul_f32 v[42:43], v[46:47], v[42:43]
	v_pk_mul_f32 v[32:33], v[36:37], v[32:33]
	v_pk_mul_f32 v[34:35], v[38:39], v[34:35]
	v_pk_mul_f32 v[24:25], v[28:29], v[24:25]
	v_pk_mul_f32 v[26:27], v[30:31], v[26:27]
	v_pk_mul_f32 v[16:17], v[20:21], v[16:17]
	v_pk_mul_f32 v[18:19], v[22:23], v[18:19]
	v_pk_mul_f32 v[8:9], v[12:13], v[8:9]
	v_pk_mul_f32 v[10:11], v[14:15], v[10:11]
	v_pk_mul_f32 v[0:1], v[4:5], v[0:1]
	v_pk_mul_f32 v[2:3], v[6:7], v[2:3]
	v_readlane_b32 s16, v253, 42
	v_lshl_or_b32 v160, s20, 7, v164
	v_readlane_b32 s17, v253, 43
	v_ashrrev_i32_e32 v161, 31, v160
	v_lshlrev_b64 v[204:205], 1, v[160:161]
	s_mov_b32 s101, 0
	v_mov_b64_e32 v[202:203], s[16:17]
	v_mad_i64_i32 v[202:203], s[22:23], v156, s6, v[202:203]
	v_lshl_add_u64 v[202:203], v[202:203], 0, v[204:205]
	s_waitcnt vmcnt(0)
	v_ffbh_u32_e32 v166, v183
	v_ffbh_u32_e32 v167, v185
	v_ffbh_u32_e32 v168, v187
	v_ffbh_u32_e32 v169, v189
	v_ffbh_u32_e32 v170, v195
	v_ffbh_u32_e32 v171, v197
	v_ffbh_u32_e32 v172, v199
	v_ffbh_u32_e32 v173, v201
	v_min_u32_e32 v166, 32, v166
	v_min_u32_e32 v167, 32, v167
	v_min_u32_e32 v168, 32, v168
	v_min_u32_e32 v169, 32, v169
	v_min_u32_e32 v170, 32, v170
	v_min_u32_e32 v171, 32, v171
	v_min_u32_e32 v172, 32, v172
	v_min_u32_e32 v173, 32, v173
	v_lshlrev_b64 v[182:183], v166, v[182:183]
	v_lshlrev_b64 v[184:185], v167, v[184:185]
	v_lshlrev_b64 v[186:187], v168, v[186:187]
	v_lshlrev_b64 v[188:189], v169, v[188:189]
	v_lshlrev_b64 v[194:195], v170, v[194:195]
	v_lshlrev_b64 v[196:197], v171, v[196:197]
	v_lshlrev_b64 v[198:199], v172, v[198:199]
	v_lshlrev_b64 v[200:201], v173, v[200:201]
	v_min_u32_e32 v182, 1, v182
	v_min_u32_e32 v184, 1, v184
	v_min_u32_e32 v186, 1, v186
	v_min_u32_e32 v188, 1, v188
	v_min_u32_e32 v194, 1, v194
	v_min_u32_e32 v196, 1, v196
	v_min_u32_e32 v198, 1, v198
	v_min_u32_e32 v200, 1, v200
	v_or_b32_e32 v182, v183, v182
	v_or_b32_e32 v184, v185, v184
	v_or_b32_e32 v186, v187, v186
	v_or_b32_e32 v188, v189, v188
	v_or_b32_e32 v194, v195, v194
	v_or_b32_e32 v196, v197, v196
	v_or_b32_e32 v198, v199, v198
	v_or_b32_e32 v200, v201, v200
	v_cvt_f32_u32_e32 v182, v182
	v_cvt_f32_u32_e32 v184, v184
	v_cvt_f32_u32_e32 v186, v186
	v_cvt_f32_u32_e32 v188, v188
	v_cvt_f32_u32_e32 v194, v194
	v_cvt_f32_u32_e32 v196, v196
	v_cvt_f32_u32_e32 v198, v198
	v_cvt_f32_u32_e32 v200, v200
	v_sub_u32_e32 v166, 32, v166
	v_sub_u32_e32 v167, 32, v167
	v_sub_u32_e32 v168, 32, v168
	v_sub_u32_e32 v169, 32, v169
	v_sub_u32_e32 v170, 32, v170
	v_sub_u32_e32 v171, 32, v171
	v_sub_u32_e32 v172, 32, v172
	v_sub_u32_e32 v173, 32, v173
	v_ldexp_f32 v166, v182, v166
	v_ldexp_f32 v167, v184, v167
	v_ldexp_f32 v168, v186, v168
	v_ldexp_f32 v169, v188, v169
	v_ldexp_f32 v170, v194, v170
	v_ldexp_f32 v171, v196, v171
	v_ldexp_f32 v172, v198, v172
	v_ldexp_f32 v173, v200, v173
	v_fmamk_f32 v166, v166, 0x2e000000, v176
	v_fmamk_f32 v167, v167, 0x2e000000, v176
	v_fmamk_f32 v168, v168, 0x2e000000, v176
	v_fmamk_f32 v169, v169, 0x2e000000, v176
	v_fmamk_f32 v170, v170, 0x2e000000, v176
	v_fmamk_f32 v171, v171, 0x2e000000, v176
	v_fmamk_f32 v172, v172, 0x2e000000, v176
	v_fmamk_f32 v173, v173, 0x2e000000, v176
	v_mul_f32_e32 v182, 0x4b800000, v166
	v_mul_f32_e32 v184, 0x4b800000, v167
	v_mul_f32_e32 v186, 0x4b800000, v168
	v_mul_f32_e32 v188, 0x4b800000, v169
	v_mul_f32_e32 v194, 0x4b800000, v170
	v_mul_f32_e32 v196, 0x4b800000, v171
	v_mul_f32_e32 v198, 0x4b800000, v172
	v_mul_f32_e32 v200, 0x4b800000, v173
	v_cmp_gt_f32_e32 vcc, s7, v166
	s_nop 1
	v_cndmask_b32_e32 v166, v166, v182, vcc
	v_rsq_f32_e32 v166, v166
	s_nop 0
	v_mul_f32_e32 v182, 0x45800000, v166
	v_cndmask_b32_e32 v166, v166, v182, vcc
	v_cmp_gt_f32_e32 vcc, s7, v167
	s_nop 1
	v_cndmask_b32_e32 v167, v167, v184, vcc
	v_rsq_f32_e32 v167, v167
	s_nop 0
	v_mul_f32_e32 v184, 0x45800000, v167
	v_cndmask_b32_e32 v167, v167, v184, vcc
	v_cmp_gt_f32_e32 vcc, s7, v168
	s_nop 1
	v_cndmask_b32_e32 v168, v168, v186, vcc
	v_rsq_f32_e32 v168, v168
	s_nop 0
	v_mul_f32_e32 v186, 0x45800000, v168
	v_cndmask_b32_e32 v168, v168, v186, vcc
	v_cmp_gt_f32_e32 vcc, s7, v169
	s_nop 1
; __device__ __forceinline__ unsigned pk2(float lo, float hi) { const f32v2_t v = {lo, hi}; const bf16v2_t b = __builtin_convertvector(v, bf16v2_t); return __builtin_bit_cast(unsigned, b); }
; #define ST_OUT(p, v) __builtin_nontemporal_store((v), (p))
;     __device__ __forceinline__ void operator()(AccRef acc, const Unit& u, int wr, int wc, int fr, int fq) const {
;     ...
;                 const float rinv = rsqrtf((float)rss[row] * (1.f / (16777216.f * DM)) + EPS);
;                 const float nrl = rinv * -1.4426950408889634f, r2 = rinv * rinv;
;                 unsigned ow[4];
; #pragma unroll
;                 for (int n = 0; n < 2; ++n)
; #pragma unroll
;                     for (int jp = 0; jp < 2; ++jp) {
;                         const f32v2_t ag = {acc[ai][0][m][n][2 * jp], acc[ai][0][m][n][2 * jp + 1]}, au = {acc[ai][1][m][n][2 * jp], acc[ai][1][m][n][2 * jp + 1]};
;                         const f32v2_t t = ag * nrl;
;                         f32v2_t e; e.x = __builtin_amdgcn_exp2f(t.x); e.y = __builtin_amdgcn_exp2f(t.y);
;                         const f32v2_t d = e + 1.0f;
;                         f32v2_t r; r.x = __builtin_amdgcn_rcpf(d.x); r.y = __builtin_amdgcn_rcpf(d.y);
;                         const f32v2_t hv = (ag * au) * (r * r2);
;                         ow[n * 2 + jp] = pk2(hv.x, hv.y);
;                     }
;                 u32x4 o; o.x = ow[0]; o.y = ow[1]; o.z = ow[2]; o.w = ow[3];
;                 ST_OUT((u32x4*)(H + (size_t)row * FF + col0), o);
	v_cndmask_b32_e32 v169, v169, v188, vcc
	v_rsq_f32_e32 v169, v169
	s_nop 0
	v_mul_f32_e32 v188, 0x45800000, v169
	v_cndmask_b32_e32 v169, v169, v188, vcc
	v_cmp_gt_f32_e32 vcc, s7, v170
	s_nop 1
	v_cndmask_b32_e32 v170, v170, v194, vcc
	v_rsq_f32_e32 v170, v170
	s_nop 0
	v_mul_f32_e32 v194, 0x45800000, v170
	v_cndmask_b32_e32 v170, v170, v194, vcc
	v_cmp_gt_f32_e32 vcc, s7, v171
	s_nop 1
	v_cndmask_b32_e32 v171, v171, v196, vcc
	v_rsq_f32_e32 v171, v171
	s_nop 0
	v_mul_f32_e32 v196, 0x45800000, v171
	v_cndmask_b32_e32 v171, v171, v196, vcc
	v_cmp_gt_f32_e32 vcc, s7, v172
	s_nop 1
	v_cndmask_b32_e32 v172, v172, v198, vcc
	v_rsq_f32_e32 v172, v172
	s_nop 0
	v_mul_f32_e32 v198, 0x45800000, v172
	v_cndmask_b32_e32 v172, v172, v198, vcc
	v_cmp_gt_f32_e32 vcc, s7, v173
	s_nop 1
	v_cndmask_b32_e32 v173, v173, v200, vcc
	v_rsq_f32_e32 v173, v173
	s_nop 0
	v_mul_f32_e32 v200, 0x45800000, v173
	v_cndmask_b32_e32 v173, v173, v200, vcc
	v_mul_f32_e32 v206, 0xbfb8aa3b, v166
	v_mul_f32_e32 v210, 0xbfb8aa3b, v167
	v_mul_f32_e32 v214, 0xbfb8aa3b, v168
	v_mul_f32_e32 v218, 0xbfb8aa3b, v169
	v_mul_f32_e32 v222, 0xbfb8aa3b, v170
	v_mul_f32_e32 v226, 0xbfb8aa3b, v171
	v_mul_f32_e32 v230, 0xbfb8aa3b, v172
	v_mul_f32_e32 v234, 0xbfb8aa3b, v173
	v_mul_f32_e32 v208, v166, v166
	v_mul_f32_e32 v212, v167, v167
	v_mul_f32_e32 v216, v168, v168
	v_mul_f32_e32 v220, v169, v169
	v_mul_f32_e32 v224, v170, v170
	v_mul_f32_e32 v228, v171, v171
	v_mul_f32_e32 v232, v172, v172
	v_mul_f32_e32 v236, v173, v173
	v_pk_mul_f32 v[124:125], v[124:125], v[206:207] op_sel_hi:[1,0]
	v_pk_mul_f32 v[126:127], v[126:127], v[206:207] op_sel_hi:[1,0]
	v_pk_mul_f32 v[116:117], v[116:117], v[206:207] op_sel_hi:[1,0]
	v_pk_mul_f32 v[118:119], v[118:119], v[206:207] op_sel_hi:[1,0]
	v_exp_f32_e32 v124, v124
	v_exp_f32_e32 v125, v125
	v_exp_f32_e32 v126, v126
	v_exp_f32_e32 v127, v127
	v_exp_f32_e32 v116, v116
	v_exp_f32_e32 v117, v117
	v_exp_f32_e32 v118, v118
	v_exp_f32_e32 v119, v119
	s_mov_b32 s100, 0x0
	v_pk_add_f32 v[124:125], v[124:125], 1.0 op_sel_hi:[1,0]
	v_pk_add_f32 v[126:127], v[126:127], 1.0 op_sel_hi:[1,0]
	v_pk_add_f32 v[116:117], v[116:117], 1.0 op_sel_hi:[1,0]
	v_pk_add_f32 v[118:119], v[118:119], 1.0 op_sel_hi:[1,0]
	v_rcp_f32_e32 v124, v124
	v_rcp_f32_e32 v125, v125
	v_rcp_f32_e32 v126, v126
	v_rcp_f32_e32 v127, v127
	v_rcp_f32_e32 v116, v116
	v_rcp_f32_e32 v117, v117
	v_rcp_f32_e32 v118, v118
	v_rcp_f32_e32 v119, v119
	v_lshl_add_u64 v[204:205], v[202:203], 0, s[100:101]
	v_pk_mul_f32 v[124:125], v[208:209], v[124:125] op_sel_hi:[0,1]
	v_pk_mul_f32 v[126:127], v[208:209], v[126:127] op_sel_hi:[0,1]
	v_pk_mul_f32 v[116:117], v[208:209], v[116:117] op_sel_hi:[0,1]
	v_pk_mul_f32 v[118:119], v[208:209], v[118:119] op_sel_hi:[0,1]
	v_pk_mul_f32 v[120:121], v[120:121], v[124:125]
	v_pk_mul_f32 v[122:123], v[122:123], v[126:127]
	v_pk_mul_f32 v[112:113], v[112:113], v[116:117]
	v_pk_mul_f32 v[114:115], v[114:115], v[118:119]
	v_cvt_pk_bf16_f32 v124, v120, v121
	v_cvt_pk_bf16_f32 v125, v122, v123
	v_cvt_pk_bf16_f32 v126, v112, v113
	v_cvt_pk_bf16_f32 v127, v114, v115
	global_store_dwordx4 v[204:205], v[124:127], off nt
	v_pk_mul_f32 v[108:109], v[108:109], v[210:211] op_sel_hi:[1,0]
	v_pk_mul_f32 v[110:111], v[110:111], v[210:211] op_sel_hi:[1,0]
	v_pk_mul_f32 v[100:101], v[100:101], v[210:211] op_sel_hi:[1,0]
	v_pk_mul_f32 v[102:103], v[102:103], v[210:211] op_sel_hi:[1,0]
	v_exp_f32_e32 v108, v108
	v_exp_f32_e32 v109, v109
	v_exp_f32_e32 v110, v110
	v_exp_f32_e32 v111, v111
	v_exp_f32_e32 v100, v100
	v_exp_f32_e32 v101, v101
	v_exp_f32_e32 v102, v102
	v_exp_f32_e32 v103, v103
	s_mov_b32 s100, 0x2c000
	v_pk_add_f32 v[108:109], v[108:109], 1.0 op_sel_hi:[1,0]
	v_pk_add_f32 v[110:111], v[110:111], 1.0 op_sel_hi:[1,0]
	v_pk_add_f32 v[100:101], v[100:101], 1.0 op_sel_hi:[1,0]
	v_pk_add_f32 v[102:103], v[102:103], 1.0 op_sel_hi:[1,0]
	v_rcp_f32_e32 v108, v108
	v_rcp_f32_e32 v109, v109
	v_rcp_f32_e32 v110, v110
	v_rcp_f32_e32 v111, v111
	v_rcp_f32_e32 v100, v100
	v_rcp_f32_e32 v101, v101
	v_rcp_f32_e32 v102, v102
	v_rcp_f32_e32 v103, v103
	v_lshl_add_u64 v[204:205], v[202:203], 0, s[100:101]
	v_pk_mul_f32 v[108:109], v[212:213], v[108:109] op_sel_hi:[0,1]
	v_pk_mul_f32 v[110:111], v[212:213], v[110:111] op_sel_hi:[0,1]
	v_pk_mul_f32 v[100:101], v[212:213], v[100:101] op_sel_hi:[0,1]
	v_pk_mul_f32 v[102:103], v[212:213], v[102:103] op_sel_hi:[0,1]
	v_pk_mul_f32 v[104:105], v[104:105], v[108:109]
	v_pk_mul_f32 v[106:107], v[106:107], v[110:111]
	v_pk_mul_f32 v[96:97], v[96:97], v[100:101]
	v_pk_mul_f32 v[98:99], v[98:99], v[102:103]
	v_cvt_pk_bf16_f32 v108, v104, v105
	v_cvt_pk_bf16_f32 v109, v106, v107
	v_cvt_pk_bf16_f32 v110, v96, v97
	v_cvt_pk_bf16_f32 v111, v98, v99
	global_store_dwordx4 v[204:205], v[108:111], off nt
	v_pk_mul_f32 v[92:93], v[92:93], v[214:215] op_sel_hi:[1,0]
	v_pk_mul_f32 v[94:95], v[94:95], v[214:215] op_sel_hi:[1,0]
	v_pk_mul_f32 v[84:85], v[84:85], v[214:215] op_sel_hi:[1,0]
	v_pk_mul_f32 v[86:87], v[86:87], v[214:215] op_sel_hi:[1,0]
	v_exp_f32_e32 v92, v92
	v_exp_f32_e32 v93, v93
	v_exp_f32_e32 v94, v94
	v_exp_f32_e32 v95, v95
	v_exp_f32_e32 v84, v84
	v_exp_f32_e32 v85, v85
	v_exp_f32_e32 v86, v86
	v_exp_f32_e32 v87, v87
	s_mov_b32 s100, 0x58000
	v_pk_add_f32 v[92:93], v[92:93], 1.0 op_sel_hi:[1,0]
	v_pk_add_f32 v[94:95], v[94:95], 1.0 op_sel_hi:[1,0]
	v_pk_add_f32 v[84:85], v[84:85], 1.0 op_sel_hi:[1,0]
	v_pk_add_f32 v[86:87], v[86:87], 1.0 op_sel_hi:[1,0]
	v_rcp_f32_e32 v92, v92
	v_rcp_f32_e32 v93, v93
	v_rcp_f32_e32 v94, v94
	v_rcp_f32_e32 v95, v95
	v_rcp_f32_e32 v84, v84
	v_rcp_f32_e32 v85, v85
	v_rcp_f32_e32 v86, v86
	v_rcp_f32_e32 v87, v87
; __device__ __forceinline__ unsigned pk2(float lo, float hi) { const f32v2_t v = {lo, hi}; const bf16v2_t b = __builtin_convertvector(v, bf16v2_t); return __builtin_bit_cast(unsigned, b); }
; #define ST_OUT(p, v) __builtin_nontemporal_store((v), (p))
;     __device__ __forceinline__ void operator()(AccRef acc, const Unit& u, int wr, int wc, int fr, int fq) const {
;     ...
;                         const f32v2_t ag = {acc[ai][0][m][n][2 * jp], acc[ai][0][m][n][2 * jp + 1]}, au = {acc[ai][1][m][n][2 * jp], acc[ai][1][m][n][2 * jp + 1]};
;                         const f32v2_t t = ag * nrl;
;                         f32v2_t e; e.x = __builtin_amdgcn_exp2f(t.x); e.y = __builtin_amdgcn_exp2f(t.y);
;                         const f32v2_t d = e + 1.0f;
;                         f32v2_t r; r.x = __builtin_amdgcn_rcpf(d.x); r.y = __builtin_amdgcn_rcpf(d.y);
;                         const f32v2_t hv = (ag * au) * (r * r2);
;                         ow[n * 2 + jp] = pk2(hv.x, hv.y);
;                     }
;                 u32x4 o; o.x = ow[0]; o.y = ow[1]; o.z = ow[2]; o.w = ow[3];
;                 ST_OUT((u32x4*)(H + (size_t)row * FF + col0), o);
	v_lshl_add_u64 v[204:205], v[202:203], 0, s[100:101]
	v_pk_mul_f32 v[92:93], v[216:217], v[92:93] op_sel_hi:[0,1]
	v_pk_mul_f32 v[94:95], v[216:217], v[94:95] op_sel_hi:[0,1]
	v_pk_mul_f32 v[84:85], v[216:217], v[84:85] op_sel_hi:[0,1]
	v_pk_mul_f32 v[86:87], v[216:217], v[86:87] op_sel_hi:[0,1]
	v_pk_mul_f32 v[88:89], v[88:89], v[92:93]
	v_pk_mul_f32 v[90:91], v[90:91], v[94:95]
	v_pk_mul_f32 v[80:81], v[80:81], v[84:85]
	v_pk_mul_f32 v[82:83], v[82:83], v[86:87]
	v_cvt_pk_bf16_f32 v92, v88, v89
	v_cvt_pk_bf16_f32 v93, v90, v91
	v_cvt_pk_bf16_f32 v94, v80, v81
	v_cvt_pk_bf16_f32 v95, v82, v83
	global_store_dwordx4 v[204:205], v[92:95], off nt
	v_pk_mul_f32 v[76:77], v[76:77], v[218:219] op_sel_hi:[1,0]
	v_pk_mul_f32 v[78:79], v[78:79], v[218:219] op_sel_hi:[1,0]
	v_pk_mul_f32 v[68:69], v[68:69], v[218:219] op_sel_hi:[1,0]
	v_pk_mul_f32 v[70:71], v[70:71], v[218:219] op_sel_hi:[1,0]
	v_exp_f32_e32 v76, v76
	v_exp_f32_e32 v77, v77
	v_exp_f32_e32 v78, v78
	v_exp_f32_e32 v79, v79
	v_exp_f32_e32 v68, v68
	v_exp_f32_e32 v69, v69
	v_exp_f32_e32 v70, v70
	v_exp_f32_e32 v71, v71
	s_mov_b32 s100, 0x84000
	v_pk_add_f32 v[76:77], v[76:77], 1.0 op_sel_hi:[1,0]
	v_pk_add_f32 v[78:79], v[78:79], 1.0 op_sel_hi:[1,0]
	v_pk_add_f32 v[68:69], v[68:69], 1.0 op_sel_hi:[1,0]
	v_pk_add_f32 v[70:71], v[70:71], 1.0 op_sel_hi:[1,0]
	v_rcp_f32_e32 v76, v76
	v_rcp_f32_e32 v77, v77
	v_rcp_f32_e32 v78, v78
	v_rcp_f32_e32 v79, v79
	v_rcp_f32_e32 v68, v68
	v_rcp_f32_e32 v69, v69
	v_rcp_f32_e32 v70, v70
	v_rcp_f32_e32 v71, v71
	v_lshl_add_u64 v[204:205], v[202:203], 0, s[100:101]
	v_pk_mul_f32 v[76:77], v[220:221], v[76:77] op_sel_hi:[0,1]
	v_pk_mul_f32 v[78:79], v[220:221], v[78:79] op_sel_hi:[0,1]
	v_pk_mul_f32 v[68:69], v[220:221], v[68:69] op_sel_hi:[0,1]
	v_pk_mul_f32 v[70:71], v[220:221], v[70:71] op_sel_hi:[0,1]
	v_pk_mul_f32 v[72:73], v[72:73], v[76:77]
	v_pk_mul_f32 v[74:75], v[74:75], v[78:79]
	v_pk_mul_f32 v[64:65], v[64:65], v[68:69]
	v_pk_mul_f32 v[66:67], v[66:67], v[70:71]
	v_cvt_pk_bf16_f32 v76, v72, v73
	v_cvt_pk_bf16_f32 v77, v74, v75
	v_cvt_pk_bf16_f32 v78, v64, v65
	v_cvt_pk_bf16_f32 v79, v66, v67
	global_store_dwordx4 v[204:205], v[76:79], off nt
	v_pk_mul_f32 v[60:61], v[60:61], v[222:223] op_sel_hi:[1,0]
	v_pk_mul_f32 v[62:63], v[62:63], v[222:223] op_sel_hi:[1,0]
	v_pk_mul_f32 v[52:53], v[52:53], v[222:223] op_sel_hi:[1,0]
	v_pk_mul_f32 v[54:55], v[54:55], v[222:223] op_sel_hi:[1,0]
	v_exp_f32_e32 v60, v60
	v_exp_f32_e32 v61, v61
	v_exp_f32_e32 v62, v62
	v_exp_f32_e32 v63, v63
	v_exp_f32_e32 v52, v52
	v_exp_f32_e32 v53, v53
	v_exp_f32_e32 v54, v54
	v_exp_f32_e32 v55, v55
	s_mov_b32 s100, 0x160000
	v_pk_add_f32 v[60:61], v[60:61], 1.0 op_sel_hi:[1,0]
	v_pk_add_f32 v[62:63], v[62:63], 1.0 op_sel_hi:[1,0]
	v_pk_add_f32 v[52:53], v[52:53], 1.0 op_sel_hi:[1,0]
	v_pk_add_f32 v[54:55], v[54:55], 1.0 op_sel_hi:[1,0]
	v_rcp_f32_e32 v60, v60
	v_rcp_f32_e32 v61, v61
	v_rcp_f32_e32 v62, v62
	v_rcp_f32_e32 v63, v63
	v_rcp_f32_e32 v52, v52
	v_rcp_f32_e32 v53, v53
	v_rcp_f32_e32 v54, v54
	v_rcp_f32_e32 v55, v55
	v_lshl_add_u64 v[204:205], v[202:203], 0, s[100:101]
	v_pk_mul_f32 v[60:61], v[224:225], v[60:61] op_sel_hi:[0,1]
	v_pk_mul_f32 v[62:63], v[224:225], v[62:63] op_sel_hi:[0,1]
	v_pk_mul_f32 v[52:53], v[224:225], v[52:53] op_sel_hi:[0,1]
	v_pk_mul_f32 v[54:55], v[224:225], v[54:55] op_sel_hi:[0,1]
	v_pk_mul_f32 v[56:57], v[56:57], v[60:61]
	v_pk_mul_f32 v[58:59], v[58:59], v[62:63]
	v_pk_mul_f32 v[48:49], v[48:49], v[52:53]
	v_pk_mul_f32 v[50:51], v[50:51], v[54:55]
	v_cvt_pk_bf16_f32 v60, v56, v57
	v_cvt_pk_bf16_f32 v61, v58, v59
	v_cvt_pk_bf16_f32 v62, v48, v49
	v_cvt_pk_bf16_f32 v63, v50, v51
	global_store_dwordx4 v[204:205], v[60:63], off nt
	v_pk_mul_f32 v[44:45], v[44:45], v[226:227] op_sel_hi:[1,0]
	v_pk_mul_f32 v[46:47], v[46:47], v[226:227] op_sel_hi:[1,0]
	v_pk_mul_f32 v[36:37], v[36:37], v[226:227] op_sel_hi:[1,0]
	v_pk_mul_f32 v[38:39], v[38:39], v[226:227] op_sel_hi:[1,0]
	v_exp_f32_e32 v44, v44
	v_exp_f32_e32 v45, v45
	v_exp_f32_e32 v46, v46
	v_exp_f32_e32 v47, v47
	v_exp_f32_e32 v36, v36
	v_exp_f32_e32 v37, v37
	v_exp_f32_e32 v38, v38
	v_exp_f32_e32 v39, v39
	s_mov_b32 s100, 0x18c000
	v_pk_add_f32 v[44:45], v[44:45], 1.0 op_sel_hi:[1,0]
; __device__ __forceinline__ unsigned pk2(float lo, float hi) { const f32v2_t v = {lo, hi}; const bf16v2_t b = __builtin_convertvector(v, bf16v2_t); return __builtin_bit_cast(unsigned, b); }
; #define ST_OUT(p, v) __builtin_nontemporal_store((v), (p))
; #define PG8_BAR __builtin_amdgcn_s_barrier()
; template <class Epi, class Sched>
; __device__ __forceinline__ void gemm_phase(LAS unsigned char* lds, const Gemm g, const Sched& S, const Epi& E) {
;     ...
;         if (!has_next) break;
; #pragma unroll
;         for (int a = 0; a < 2; ++a)
; #pragma unroll
;             for (int b = 0; b < 2; ++b)
; #pragma unroll
;                 for (int m = 0; m < 4; ++m)
; #pragma unroll
;                     for (int n = 0; n < 2; ++n) acc[a][b][m][n] = (f32x4){0.f, 0.f, 0.f, 0.f};
;         cur = nxt; cA = nA; cB = nB; ++ui;
;         if (Sched::SEGMENTED) nt = S.nt(cur);
;     ...
;         if (wr == 1) PG8_BAR;
;     __device__ __forceinline__ void operator()(AccRef acc, const Unit& u, int wr, int wc, int fr, int fq) const {
;     ...
;                         const f32v2_t ag = {acc[ai][0][m][n][2 * jp], acc[ai][0][m][n][2 * jp + 1]}, au = {acc[ai][1][m][n][2 * jp], acc[ai][1][m][n][2 * jp + 1]};
;                         const f32v2_t t = ag * nrl;
;                         f32v2_t e; e.x = __builtin_amdgcn_exp2f(t.x); e.y = __builtin_amdgcn_exp2f(t.y);
;                         const f32v2_t d = e + 1.0f;
;                         f32v2_t r; r.x = __builtin_amdgcn_rcpf(d.x); r.y = __builtin_amdgcn_rcpf(d.y);
;                         const f32v2_t hv = (ag * au) * (r * r2);
;                         ow[n * 2 + jp] = pk2(hv.x, hv.y);
;                     }
;                 u32x4 o; o.x = ow[0]; o.y = ow[1]; o.z = ow[2]; o.w = ow[3];
;                 ST_OUT((u32x4*)(H + (size_t)row * FF + col0), o);
	v_pk_add_f32 v[46:47], v[46:47], 1.0 op_sel_hi:[1,0]
	v_pk_add_f32 v[36:37], v[36:37], 1.0 op_sel_hi:[1,0]
	v_pk_add_f32 v[38:39], v[38:39], 1.0 op_sel_hi:[1,0]
	v_rcp_f32_e32 v44, v44
	v_rcp_f32_e32 v45, v45
	v_rcp_f32_e32 v46, v46
	v_rcp_f32_e32 v47, v47
	v_rcp_f32_e32 v36, v36
	v_rcp_f32_e32 v37, v37
	v_rcp_f32_e32 v38, v38
	v_rcp_f32_e32 v39, v39
	v_lshl_add_u64 v[204:205], v[202:203], 0, s[100:101]
	v_pk_mul_f32 v[44:45], v[228:229], v[44:45] op_sel_hi:[0,1]
	v_pk_mul_f32 v[46:47], v[228:229], v[46:47] op_sel_hi:[0,1]
	v_pk_mul_f32 v[36:37], v[228:229], v[36:37] op_sel_hi:[0,1]
	v_pk_mul_f32 v[38:39], v[228:229], v[38:39] op_sel_hi:[0,1]
	v_pk_mul_f32 v[40:41], v[40:41], v[44:45]
	v_pk_mul_f32 v[42:43], v[42:43], v[46:47]
	v_pk_mul_f32 v[32:33], v[32:33], v[36:37]
	v_pk_mul_f32 v[34:35], v[34:35], v[38:39]
	v_cvt_pk_bf16_f32 v44, v40, v41
	v_cvt_pk_bf16_f32 v45, v42, v43
	v_cvt_pk_bf16_f32 v46, v32, v33
	v_cvt_pk_bf16_f32 v47, v34, v35
	global_store_dwordx4 v[204:205], v[44:47], off nt
	v_pk_mul_f32 v[28:29], v[28:29], v[230:231] op_sel_hi:[1,0]
	v_pk_mul_f32 v[30:31], v[30:31], v[230:231] op_sel_hi:[1,0]
	v_pk_mul_f32 v[20:21], v[20:21], v[230:231] op_sel_hi:[1,0]
	v_pk_mul_f32 v[22:23], v[22:23], v[230:231] op_sel_hi:[1,0]
	v_exp_f32_e32 v28, v28
	v_exp_f32_e32 v29, v29
	v_exp_f32_e32 v30, v30
	v_exp_f32_e32 v31, v31
	v_exp_f32_e32 v20, v20
	v_exp_f32_e32 v21, v21
	v_exp_f32_e32 v22, v22
	v_exp_f32_e32 v23, v23
	s_mov_b32 s100, 0x1b8000
	v_pk_add_f32 v[28:29], v[28:29], 1.0 op_sel_hi:[1,0]
	v_pk_add_f32 v[30:31], v[30:31], 1.0 op_sel_hi:[1,0]
	v_pk_add_f32 v[20:21], v[20:21], 1.0 op_sel_hi:[1,0]
	v_pk_add_f32 v[22:23], v[22:23], 1.0 op_sel_hi:[1,0]
	v_rcp_f32_e32 v28, v28
	v_rcp_f32_e32 v29, v29
	v_rcp_f32_e32 v30, v30
	v_rcp_f32_e32 v31, v31
	v_rcp_f32_e32 v20, v20
	v_rcp_f32_e32 v21, v21
	v_rcp_f32_e32 v22, v22
	v_rcp_f32_e32 v23, v23
	v_lshl_add_u64 v[204:205], v[202:203], 0, s[100:101]
	v_pk_mul_f32 v[28:29], v[232:233], v[28:29] op_sel_hi:[0,1]
	v_pk_mul_f32 v[30:31], v[232:233], v[30:31] op_sel_hi:[0,1]
	v_pk_mul_f32 v[20:21], v[232:233], v[20:21] op_sel_hi:[0,1]
	v_pk_mul_f32 v[22:23], v[232:233], v[22:23] op_sel_hi:[0,1]
	v_pk_mul_f32 v[24:25], v[24:25], v[28:29]
	v_pk_mul_f32 v[26:27], v[26:27], v[30:31]
	v_pk_mul_f32 v[16:17], v[16:17], v[20:21]
	v_pk_mul_f32 v[18:19], v[18:19], v[22:23]
	v_cvt_pk_bf16_f32 v28, v24, v25
	v_cvt_pk_bf16_f32 v29, v26, v27
	v_cvt_pk_bf16_f32 v30, v16, v17
	v_cvt_pk_bf16_f32 v31, v18, v19
	global_store_dwordx4 v[204:205], v[28:31], off nt
	v_pk_mul_f32 v[12:13], v[12:13], v[234:235] op_sel_hi:[1,0]
	v_pk_mul_f32 v[14:15], v[14:15], v[234:235] op_sel_hi:[1,0]
	v_pk_mul_f32 v[4:5], v[4:5], v[234:235] op_sel_hi:[1,0]
	v_pk_mul_f32 v[6:7], v[6:7], v[234:235] op_sel_hi:[1,0]
	v_exp_f32_e32 v12, v12
	v_exp_f32_e32 v13, v13
	v_exp_f32_e32 v14, v14
	v_exp_f32_e32 v15, v15
	v_exp_f32_e32 v4, v4
	v_exp_f32_e32 v5, v5
	v_exp_f32_e32 v6, v6
	v_exp_f32_e32 v7, v7
	s_mov_b32 s100, 0x1e4000
	v_pk_add_f32 v[12:13], v[12:13], 1.0 op_sel_hi:[1,0]
	v_pk_add_f32 v[14:15], v[14:15], 1.0 op_sel_hi:[1,0]
	v_pk_add_f32 v[4:5], v[4:5], 1.0 op_sel_hi:[1,0]
	v_pk_add_f32 v[6:7], v[6:7], 1.0 op_sel_hi:[1,0]
	v_rcp_f32_e32 v12, v12
	v_rcp_f32_e32 v13, v13
	v_rcp_f32_e32 v14, v14
	v_rcp_f32_e32 v15, v15
	v_rcp_f32_e32 v4, v4
	v_rcp_f32_e32 v5, v5
	v_rcp_f32_e32 v6, v6
	v_rcp_f32_e32 v7, v7
	v_lshl_add_u64 v[204:205], v[202:203], 0, s[100:101]
	v_pk_mul_f32 v[12:13], v[236:237], v[12:13] op_sel_hi:[0,1]
	v_pk_mul_f32 v[14:15], v[236:237], v[14:15] op_sel_hi:[0,1]
	v_pk_mul_f32 v[4:5], v[236:237], v[4:5] op_sel_hi:[0,1]
	v_pk_mul_f32 v[6:7], v[236:237], v[6:7] op_sel_hi:[0,1]
	v_pk_mul_f32 v[8:9], v[8:9], v[12:13]
	v_pk_mul_f32 v[10:11], v[10:11], v[14:15]
	v_pk_mul_f32 v[0:1], v[0:1], v[4:5]
	v_pk_mul_f32 v[2:3], v[2:3], v[6:7]
	v_cvt_pk_bf16_f32 v12, v8, v9
	v_cvt_pk_bf16_f32 v13, v10, v11
	v_cvt_pk_bf16_f32 v14, v0, v1
	v_cvt_pk_bf16_f32 v15, v2, v3
	global_store_dwordx4 v[204:205], v[12:15], off nt
	s_movk_i32 s92, 0x37ff
	s_andn2_b64 vcc, exec, s[38:39]
	s_mov_b64 s[22:23], -1
	s_cbranch_vccnz .LBB0_741
	s_andn2_b64 vcc, exec, s[0:1]
	s_cbranch_vccnz .LBB0_740
	s_barrier
	s_branch .LBB0_740
